# GEMM4 (both layers) converted to the 128x256 pair-tile LDS-DMA mainloop (K=2816), compiler residual epilogue reused twice
# speedup vs baseline: 1.0277x; 1.0277x over previous
.Lg1a_cont:
	s_lshl3_add_u32 s22, s5, s25
	s_lshl_b32 s23, s6, 1
	s_mul_i32 s0, s22, 0x40000
	s_add_u32 s14, s44, s0
	s_addc_u32 s15, s45, 0
	s_mul_i32 s0, s23, 0x40000
	s_add_u32 s16, s48, s0
	s_addc_u32 s17, s49, 0
	s_add_u32 s18, s16, 0x40000
	s_addc_u32 s19, s17, 0
	s_waitcnt vmcnt(0) lgkmcnt(0)
	s_barrier
	s_add_u32 m0, s20, 0x0
	s_nop 0
	global_load_lds_dwordx4 v160, s[14:15]
	global_load_lds_dwordx4 v160, s[14:15] offset:1024
	s_add_u32 s14, s14, 0x2000
	s_addc_u32 s15, s15, 0
	s_add_u32 m0, s20, 0x2000
	s_nop 0
	global_load_lds_dwordx4 v160, s[16:17]
	global_load_lds_dwordx4 v160, s[16:17] offset:1024
	s_add_u32 s16, s16, 0x2000
	s_addc_u32 s17, s17, 0
	s_add_u32 m0, s20, 0x4000
	s_nop 0
	global_load_lds_dwordx4 v160, s[18:19]
	global_load_lds_dwordx4 v160, s[18:19] offset:1024
	s_add_u32 s18, s18, 0x2000
	s_addc_u32 s19, s19, 0
	s_waitcnt vmcnt(0)
	s_barrier
	s_add_u32 m0, s20, 0x6000
	s_nop 0
	global_load_lds_dwordx4 v160, s[14:15]
	global_load_lds_dwordx4 v160, s[14:15] offset:1024
	s_add_u32 s14, s14, 0x2000
	s_addc_u32 s15, s15, 0
	s_add_u32 m0, s20, 0x8000
	s_nop 0
	global_load_lds_dwordx4 v160, s[16:17]
	global_load_lds_dwordx4 v160, s[16:17] offset:1024
	s_add_u32 s16, s16, 0x2000
	s_addc_u32 s17, s17, 0
	s_add_u32 m0, s20, 0xa400
	s_nop 0
	global_load_lds_dwordx4 v160, s[18:19]
	global_load_lds_dwordx4 v160, s[18:19] offset:1024
	s_add_u32 s18, s18, 0x2000
	s_addc_u32 s19, s19, 0
	ds_read_b128 v[64:67], v154 offset:0
	ds_read_b128 v[72:75], v156 offset:8192
	ds_read_b128 v[76:79], v156 offset:10240
	ds_read_b128 v[80:83], v156 offset:16384
	ds_read_b128 v[150:153], v156 offset:18432
	ds_read_b128 v[68:71], v154 offset:2048
	s_waitcnt lgkmcnt(4)
	v_mfma_f32_32x32x16_bf16 v[48:63], v[64:67], v[72:75], 0
	s_waitcnt lgkmcnt(3)
	v_mfma_f32_32x32x16_bf16 v[32:47], v[64:67], v[76:79], 0
	s_waitcnt lgkmcnt(2)
	v_mfma_f32_32x32x16_bf16 v[132:147], v[64:67], v[80:83], 0
	s_waitcnt lgkmcnt(1)
	v_mfma_f32_32x32x16_bf16 v[116:131], v[64:67], v[150:153], 0
	ds_read_b128 v[64:67], v155 offset:0
	s_waitcnt lgkmcnt(1)
	v_mfma_f32_32x32x16_bf16 v[84:99], v[68:71], v[150:153], 0
	ds_read_b128 v[150:153], v157 offset:18432
	v_mfma_f32_32x32x16_bf16 v[100:115], v[68:71], v[80:83], 0
	ds_read_b128 v[80:83], v157 offset:16384
	v_mfma_f32_32x32x16_bf16 v[0:15], v[68:71], v[76:79], 0
	ds_read_b128 v[76:79], v157 offset:10240
	v_mfma_f32_32x32x16_bf16 v[16:31], v[68:71], v[72:75], 0
	ds_read_b128 v[72:75], v157 offset:8192
	ds_read_b128 v[68:71], v155 offset:2048
	s_waitcnt lgkmcnt(4)
	v_mfma_f32_32x32x16_bf16 v[116:131], v[64:67], v[150:153], v[116:131]
	s_waitcnt lgkmcnt(3)
	v_mfma_f32_32x32x16_bf16 v[132:147], v[64:67], v[80:83], v[132:147]
	s_waitcnt lgkmcnt(2)
	v_mfma_f32_32x32x16_bf16 v[32:47], v[64:67], v[76:79], v[32:47]
	s_waitcnt lgkmcnt(1)
	v_mfma_f32_32x32x16_bf16 v[48:63], v[64:67], v[72:75], v[48:63]
	s_waitcnt vmcnt(0) lgkmcnt(0)
	s_barrier
	ds_read_b128 v[64:67], v154 offset:24576
	s_add_u32 m0, s20, 0x0
	s_nop 0
	global_load_lds_dwordx4 v160, s[14:15]
	global_load_lds_dwordx4 v160, s[14:15] offset:1024
	s_add_u32 s14, s14, 0x2000
	s_addc_u32 s15, s15, 0
	v_mfma_f32_32x32x16_bf16 v[16:31], v[68:71], v[72:75], v[16:31]
	ds_read_b128 v[72:75], v156 offset:32768
	s_add_u32 m0, s20, 0x2000
	s_nop 0
	global_load_lds_dwordx4 v160, s[16:17]
	global_load_lds_dwordx4 v160, s[16:17] offset:1024
	s_add_u32 s16, s16, 0x2000
	s_addc_u32 s17, s17, 0
	v_mfma_f32_32x32x16_bf16 v[0:15], v[68:71], v[76:79], v[0:15]
	ds_read_b128 v[76:79], v156 offset:34816
	s_add_u32 m0, s20, 0x4000
	s_nop 0
	global_load_lds_dwordx4 v160, s[18:19]
	global_load_lds_dwordx4 v160, s[18:19] offset:1024
	s_add_u32 s18, s18, 0x2000
	s_addc_u32 s19, s19, 0
	v_mfma_f32_32x32x16_bf16 v[100:115], v[68:71], v[80:83], v[100:115]
	ds_read_b128 v[80:83], v156 offset:41984
	v_mfma_f32_32x32x16_bf16 v[84:99], v[68:71], v[150:153], v[84:99]
	ds_read_b128 v[150:153], v156 offset:44032
	ds_read_b128 v[68:71], v154 offset:26624
	s_waitcnt lgkmcnt(4)
	v_mfma_f32_32x32x16_bf16 v[48:63], v[64:67], v[72:75], v[48:63]
	s_waitcnt lgkmcnt(3)
	v_mfma_f32_32x32x16_bf16 v[32:47], v[64:67], v[76:79], v[32:47]
	s_waitcnt lgkmcnt(2)
	v_mfma_f32_32x32x16_bf16 v[132:147], v[64:67], v[80:83], v[132:147]
	s_waitcnt lgkmcnt(1)
	v_mfma_f32_32x32x16_bf16 v[116:131], v[64:67], v[150:153], v[116:131]
	ds_read_b128 v[64:67], v155 offset:24576
	s_waitcnt lgkmcnt(1)
	v_mfma_f32_32x32x16_bf16 v[84:99], v[68:71], v[150:153], v[84:99]
	ds_read_b128 v[150:153], v157 offset:44032
	v_mfma_f32_32x32x16_bf16 v[100:115], v[68:71], v[80:83], v[100:115]
	ds_read_b128 v[80:83], v157 offset:41984
	v_mfma_f32_32x32x16_bf16 v[0:15], v[68:71], v[76:79], v[0:15]
	ds_read_b128 v[76:79], v157 offset:34816
	v_mfma_f32_32x32x16_bf16 v[16:31], v[68:71], v[72:75], v[16:31]
	ds_read_b128 v[72:75], v157 offset:32768
	ds_read_b128 v[68:71], v155 offset:26624
	s_waitcnt lgkmcnt(4)
	v_mfma_f32_32x32x16_bf16 v[116:131], v[64:67], v[150:153], v[116:131]
	s_waitcnt lgkmcnt(3)
	v_mfma_f32_32x32x16_bf16 v[132:147], v[64:67], v[80:83], v[132:147]
	s_waitcnt lgkmcnt(2)
	v_mfma_f32_32x32x16_bf16 v[32:47], v[64:67], v[76:79], v[32:47]
	s_waitcnt lgkmcnt(1)
	v_mfma_f32_32x32x16_bf16 v[48:63], v[64:67], v[72:75], v[48:63]
	s_waitcnt vmcnt(0) lgkmcnt(0)
	s_barrier
	ds_read_b128 v[64:67], v154 offset:0
	s_add_u32 m0, s20, 0x6000
	s_nop 0
	global_load_lds_dwordx4 v160, s[14:15]
	global_load_lds_dwordx4 v160, s[14:15] offset:1024
	s_add_u32 s14, s14, 0x2000
	s_addc_u32 s15, s15, 0
	v_mfma_f32_32x32x16_bf16 v[16:31], v[68:71], v[72:75], v[16:31]
	ds_read_b128 v[72:75], v156 offset:8192
	s_add_u32 m0, s20, 0x8000
	s_nop 0
	global_load_lds_dwordx4 v160, s[16:17]
	global_load_lds_dwordx4 v160, s[16:17] offset:1024
	s_add_u32 s16, s16, 0x2000
	s_addc_u32 s17, s17, 0
	v_mfma_f32_32x32x16_bf16 v[0:15], v[68:71], v[76:79], v[0:15]
	ds_read_b128 v[76:79], v156 offset:10240
	s_add_u32 m0, s20, 0xa400
	s_nop 0
	global_load_lds_dwordx4 v160, s[18:19]
	global_load_lds_dwordx4 v160, s[18:19] offset:1024
	s_add_u32 s18, s18, 0x2000
	s_addc_u32 s19, s19, 0
	v_mfma_f32_32x32x16_bf16 v[100:115], v[68:71], v[80:83], v[100:115]
	ds_read_b128 v[80:83], v156 offset:16384
	v_mfma_f32_32x32x16_bf16 v[84:99], v[68:71], v[150:153], v[84:99]
	ds_read_b128 v[150:153], v156 offset:18432
	ds_read_b128 v[68:71], v154 offset:2048
	s_mov_b32 s21, 14

.Lg3a_cont:
	s_lshl3_add_u32 s22, s12, s25
	s_lshl_b32 s23, s13, 1
	s_mul_i32 s8, s22, 0x40000
	s_add_u32 s14, s44, s8
	s_addc_u32 s15, s45, 0
	s_mul_i32 s8, s23, 0x40000
	s_add_u32 s8, s8, 0xd80000
	s_add_u32 s16, s48, s8
	s_addc_u32 s17, s49, 0
	s_add_u32 s18, s16, 0x40000
	s_addc_u32 s19, s17, 0
	s_waitcnt vmcnt(0) lgkmcnt(0)
	s_barrier
	s_add_u32 m0, s20, 0x0
	s_nop 0
	global_load_lds_dwordx4 v164, s[14:15]
	global_load_lds_dwordx4 v164, s[14:15] offset:1024
	s_add_u32 s14, s14, 0x2000
	s_addc_u32 s15, s15, 0
	s_add_u32 m0, s20, 0x2000
	s_nop 0
	global_load_lds_dwordx4 v164, s[16:17]
	global_load_lds_dwordx4 v164, s[16:17] offset:1024
	s_add_u32 s16, s16, 0x2000
	s_addc_u32 s17, s17, 0
	s_add_u32 m0, s20, 0x4000
	s_nop 0
	global_load_lds_dwordx4 v164, s[18:19]
	global_load_lds_dwordx4 v164, s[18:19] offset:1024
	s_add_u32 s18, s18, 0x2000
	s_addc_u32 s19, s19, 0
	s_waitcnt vmcnt(0)
	s_barrier
	s_add_u32 m0, s20, 0x6000
	s_nop 0
	global_load_lds_dwordx4 v164, s[14:15]
	global_load_lds_dwordx4 v164, s[14:15] offset:1024
	s_add_u32 s14, s14, 0x2000
	s_addc_u32 s15, s15, 0
	s_add_u32 m0, s20, 0x8000
	s_nop 0
	global_load_lds_dwordx4 v164, s[16:17]
	global_load_lds_dwordx4 v164, s[16:17] offset:1024
	s_add_u32 s16, s16, 0x2000
	s_addc_u32 s17, s17, 0
	s_add_u32 m0, s20, 0xa400
	s_nop 0
	global_load_lds_dwordx4 v164, s[18:19]
	global_load_lds_dwordx4 v164, s[18:19] offset:1024
	s_add_u32 s18, s18, 0x2000
	s_addc_u32 s19, s19, 0
	ds_read_b128 v[82:85], v160 offset:0
	ds_read_b128 v[138:141], v162 offset:8192
	ds_read_b128 v[142:145], v162 offset:10240
	ds_read_b128 v[150:153], v162 offset:16384
	ds_read_b128 v[154:157], v162 offset:18432
	ds_read_b128 v[134:137], v160 offset:2048
	s_waitcnt lgkmcnt(4)
	v_mfma_f32_32x32x16_bf16 v[32:47], v[82:85], v[138:141], 0
	s_waitcnt lgkmcnt(3)
	v_mfma_f32_32x32x16_bf16 v[48:63], v[82:85], v[142:145], 0
	s_waitcnt lgkmcnt(2)
	v_mfma_f32_32x32x16_bf16 v[86:101], v[82:85], v[150:153], 0
	s_waitcnt lgkmcnt(1)
	v_mfma_f32_32x32x16_bf16 v[102:117], v[82:85], v[154:157], 0
	ds_read_b128 v[82:85], v161 offset:0
	s_waitcnt lgkmcnt(1)
	v_mfma_f32_32x32x16_bf16 v[66:81], v[134:137], v[154:157], 0
	ds_read_b128 v[154:157], v163 offset:18432
	v_mfma_f32_32x32x16_bf16 v[118:133], v[134:137], v[150:153], 0
	ds_read_b128 v[150:153], v163 offset:16384
	v_mfma_f32_32x32x16_bf16 v[16:31], v[134:137], v[142:145], 0
	ds_read_b128 v[142:145], v163 offset:10240
	v_mfma_f32_32x32x16_bf16 v[0:15], v[134:137], v[138:141], 0
	ds_read_b128 v[138:141], v163 offset:8192
	ds_read_b128 v[134:137], v161 offset:2048
	s_waitcnt lgkmcnt(4)
	v_mfma_f32_32x32x16_bf16 v[102:117], v[82:85], v[154:157], v[102:117]
	s_waitcnt lgkmcnt(3)
	v_mfma_f32_32x32x16_bf16 v[86:101], v[82:85], v[150:153], v[86:101]
	s_waitcnt lgkmcnt(2)
	v_mfma_f32_32x32x16_bf16 v[48:63], v[82:85], v[142:145], v[48:63]
	s_waitcnt lgkmcnt(1)
	v_mfma_f32_32x32x16_bf16 v[32:47], v[82:85], v[138:141], v[32:47]
	s_waitcnt vmcnt(0) lgkmcnt(0)
	s_barrier
	ds_read_b128 v[82:85], v160 offset:24576
	s_add_u32 m0, s20, 0x0
	s_nop 0
	global_load_lds_dwordx4 v164, s[14:15]
	global_load_lds_dwordx4 v164, s[14:15] offset:1024
	s_add_u32 s14, s14, 0x2000
	s_addc_u32 s15, s15, 0
	v_mfma_f32_32x32x16_bf16 v[0:15], v[134:137], v[138:141], v[0:15]
	ds_read_b128 v[138:141], v162 offset:32768
	s_add_u32 m0, s20, 0x2000
	s_nop 0
	global_load_lds_dwordx4 v164, s[16:17]
	global_load_lds_dwordx4 v164, s[16:17] offset:1024
	s_add_u32 s16, s16, 0x2000
	s_addc_u32 s17, s17, 0
	v_mfma_f32_32x32x16_bf16 v[16:31], v[134:137], v[142:145], v[16:31]
	ds_read_b128 v[142:145], v162 offset:34816
	s_add_u32 m0, s20, 0x4000
	s_nop 0
	global_load_lds_dwordx4 v164, s[18:19]
	global_load_lds_dwordx4 v164, s[18:19] offset:1024
	s_add_u32 s18, s18, 0x2000
	s_addc_u32 s19, s19, 0
	v_mfma_f32_32x32x16_bf16 v[118:133], v[134:137], v[150:153], v[118:133]
	ds_read_b128 v[150:153], v162 offset:41984
	v_mfma_f32_32x32x16_bf16 v[66:81], v[134:137], v[154:157], v[66:81]
	ds_read_b128 v[154:157], v162 offset:44032
	ds_read_b128 v[134:137], v160 offset:26624
	s_waitcnt lgkmcnt(4)
	v_mfma_f32_32x32x16_bf16 v[32:47], v[82:85], v[138:141], v[32:47]
	s_waitcnt lgkmcnt(3)
	v_mfma_f32_32x32x16_bf16 v[48:63], v[82:85], v[142:145], v[48:63]
	s_waitcnt lgkmcnt(2)
	v_mfma_f32_32x32x16_bf16 v[86:101], v[82:85], v[150:153], v[86:101]
	s_waitcnt lgkmcnt(1)
	v_mfma_f32_32x32x16_bf16 v[102:117], v[82:85], v[154:157], v[102:117]
	ds_read_b128 v[82:85], v161 offset:24576
	s_waitcnt lgkmcnt(1)
	v_mfma_f32_32x32x16_bf16 v[66:81], v[134:137], v[154:157], v[66:81]
	ds_read_b128 v[154:157], v163 offset:44032
	v_mfma_f32_32x32x16_bf16 v[118:133], v[134:137], v[150:153], v[118:133]
	ds_read_b128 v[150:153], v163 offset:41984
	v_mfma_f32_32x32x16_bf16 v[16:31], v[134:137], v[142:145], v[16:31]
	ds_read_b128 v[142:145], v163 offset:34816
	v_mfma_f32_32x32x16_bf16 v[0:15], v[134:137], v[138:141], v[0:15]
	ds_read_b128 v[138:141], v163 offset:32768
	ds_read_b128 v[134:137], v161 offset:26624
	s_waitcnt lgkmcnt(4)
	v_mfma_f32_32x32x16_bf16 v[102:117], v[82:85], v[154:157], v[102:117]
	s_waitcnt lgkmcnt(3)
	v_mfma_f32_32x32x16_bf16 v[86:101], v[82:85], v[150:153], v[86:101]
	s_waitcnt lgkmcnt(2)
	v_mfma_f32_32x32x16_bf16 v[48:63], v[82:85], v[142:145], v[48:63]
	s_waitcnt lgkmcnt(1)
	v_mfma_f32_32x32x16_bf16 v[32:47], v[82:85], v[138:141], v[32:47]
	s_waitcnt vmcnt(0) lgkmcnt(0)
	s_barrier
	ds_read_b128 v[82:85], v160 offset:0
	s_add_u32 m0, s20, 0x6000
	s_nop 0
	global_load_lds_dwordx4 v164, s[14:15]
	global_load_lds_dwordx4 v164, s[14:15] offset:1024
	s_add_u32 s14, s14, 0x2000
	s_addc_u32 s15, s15, 0
	v_mfma_f32_32x32x16_bf16 v[0:15], v[134:137], v[138:141], v[0:15]
	ds_read_b128 v[138:141], v162 offset:8192
	s_add_u32 m0, s20, 0x8000
	s_nop 0
	global_load_lds_dwordx4 v164, s[16:17]
	global_load_lds_dwordx4 v164, s[16:17] offset:1024
	s_add_u32 s16, s16, 0x2000
	s_addc_u32 s17, s17, 0
	v_mfma_f32_32x32x16_bf16 v[16:31], v[134:137], v[142:145], v[16:31]
	ds_read_b128 v[142:145], v162 offset:10240
	s_add_u32 m0, s20, 0xa400
	s_nop 0
	global_load_lds_dwordx4 v164, s[18:19]
	global_load_lds_dwordx4 v164, s[18:19] offset:1024
	s_add_u32 s18, s18, 0x2000
	s_addc_u32 s19, s19, 0
	v_mfma_f32_32x32x16_bf16 v[118:133], v[134:137], v[150:153], v[118:133]
	ds_read_b128 v[150:153], v162 offset:16384
	v_mfma_f32_32x32x16_bf16 v[66:81], v[134:137], v[154:157], v[66:81]
	ds_read_b128 v[154:157], v162 offset:18432
	ds_read_b128 v[134:137], v160 offset:2048
	s_mov_b32 s21, 14

.LBB0_614:
	s_or_b64 exec, exec, s[2:3]
	s_add_u32 s0, s48, 0x1880000
	s_addc_u32 s1, s49, 0
	v_mov_b32_e32 v144, v148
	s_mov_b32 s8, s55
	s_waitcnt lgkmcnt(0)
	s_barrier
	v_writelane_b32 v158, s0, 26
	s_mov_b32 s9, s94
	s_cmpk_gt_i32 s8, 0x827
	v_writelane_b32 v158, s1, 27
	s_cbranch_scc1 .LBB0_637
	s_waitcnt vmcnt(0)
	v_ashrrev_i32_e32 v8, 2, v144
	v_lshlrev_b32_e32 v0, 5, v8
	v_ashrrev_i32_e32 v1, 31, v0
	v_lshlrev_b64 v[2:3], 1, v[0:1]
	v_lshlrev_b32_e32 v0, 4, v144
	v_and_b32_e32 v6, 48, v0
	v_mov_b32_e32 v0, 0
	v_readlane_b32 s0, v158, 26
	v_lshl_add_u64 v[4:5], s[46:47], 0, v[2:3]
	v_mov_b32_e32 v7, v0
	v_readlane_b32 s1, v158, 27
	v_lshl_add_u64 v[132:133], v[4:5], 0, v[6:7]
	v_mov_b32_e32 v145, 0xb0000
	v_lshl_add_u64 v[4:5], s[0:1], 0, v[2:3]
	v_lshl_add_u64 v[134:135], v[4:5], 0, v[6:7]
	v_lshrrev_b32_e32 v4, 1, v144
	v_and_b32_e32 v7, 31, v144
	s_mov_b32 s1, 0xfffffc0
	s_movk_i32 s0, 0x50
	v_and_b32_e32 v5, 16, v4
	v_and_or_b32 v4, v4, s1, v7
	v_and_b32_e32 v7, 0x5f, v144
	v_mul_lo_u32 v1, v8, s0
	v_mul_lo_u32 v4, v4, s0
	v_mul_u32_u24_e32 v7, 0x50, v7
	v_or_b32_e32 v2, v2, v6
	v_lshl_add_u64 v[136:137], s[48:49], 0, v[2:3]
	s_movk_i32 s10, 0x2000
	s_movk_i32 s11, 0x4000
	s_movk_i32 s12, 0x5000
	v_add_u32_e32 v146, v1, v6
	v_add_u32_e32 v147, v5, v4
	v_add_u32_e32 v150, v5, v7
	s_movk_i32 s13, 0x210
	v_and_b32_e32 v142, 63, v148
	v_lshrrev_b32_e32 v143, 6, v148
	v_and_b32_e32 v154, 31, v142
	v_lshlrev_b32_e32 v154, 6, v154
	v_lshrrev_b32_e32 v155, 5, v142
	v_bfe_u32 v156, v142, 2, 2
	v_xor_b32_e32 v155, v155, v156
	v_lshl_add_u32 v154, v155, 4, v154
	v_lshrrev_b32_e32 v155, 1, v143
	v_lshl_add_u32 v81, v155, 12, v154
	v_and_b32_e32 v155, 1, v143
	v_lshl_add_u32 v146, v155, 12, v154
	v_xor_b32_e32 v145, 32, v81
	v_xor_b32_e32 v147, 32, v146
	v_lshrrev_b32_e32 v154, 2, v142
	v_lshlrev_b32_e32 v154, 6, v154
	v_and_b32_e32 v155, 3, v142
	v_bfe_u32 v156, v142, 4, 2
	v_xor_b32_e32 v155, v155, v156
	v_lshl_add_u32 v154, v155, 4, v154
	v_lshl_add_u32 v157, v143, 11, v154
	v_readfirstlane_b32 s28, v143
	s_lshl_b32 s28, s28, 11
	s_and_b32 s33, s8, 7
	s_lshr_b32 s8, s8, 3
	s_lshr_b32 s56, s9, 3
	s_sub_u32 s57, 268, s33
	s_lshr_b32 s57, s57, 3
	s_mul_i32 s57, s57, 4
	s_branch .Lg4a_hdr
.LBB0_616:
.Lg4a_epi:
	v_mov_b32_e32 v0, 0
	s_waitcnt vmcnt(3)
	v_mov_b32_e32 v80, v144
	s_lshl_b32 s0, s14, 7
	v_lshlrev_b32_e32 v1, 3, v80
	v_lshrrev_b32_e32 v5, 2, v80
	s_waitcnt vmcnt(2)
	v_and_b32_e32 v8, 0x78, v1
	v_lshrrev_b32_e32 v4, 3, v80
	v_and_b32_e32 v5, 0xfffffe0, v5
	v_lshl_or_b32 v1, s15, 7, v8
	v_and_or_b32 v4, v4, 4, v5
	v_ashrrev_i32_e32 v2, 5, v1
	v_and_b32_e32 v1, 0x5f, v80
	v_mul_lo_u32 v4, v4, s13
	v_lshl_add_u32 v1, v1, 2, v4
	v_ashrrev_i32_e32 v4, 3, v80
	v_and_b32_e32 v5, 64, v4
	v_add_u32_e32 v4, s0, v4
	v_ashrrev_i32_e32 v3, 31, v2
	v_ashrrev_i32_e32 v9, 4, v80
	v_ashrrev_i32_e32 v4, 7, v4
	v_lshlrev_b64 v[2:3], 13, v[2:3]
	v_and_or_b32 v6, v9, 31, v5
	v_ashrrev_i32_e32 v5, 31, v4
	s_waitcnt vmcnt(1)
	v_lshl_add_u64 v[10:11], s[44:45], 0, v[2:3]
	v_lshlrev_b64 v[2:3], 18, v[4:5]
	ds_write2_b32 v1, v64, v48 offset1:32
	ds_write2_b32 v1, v65, v49 offset0:132 offset1:164
	v_add_u32_e32 v49, 0x400, v1
	v_add_u32_e32 v64, 0x1000, v1
	v_lshl_add_u64 v[2:3], v[10:11], 0, v[2:3]
	v_lshlrev_b32_e32 v4, 6, v6
	v_mov_b32_e32 v5, v0
	ds_write2_b32 v49, v66, v50 offset0:8 offset1:40
	ds_write2_b32 v49, v67, v51 offset0:140 offset1:172
	ds_write2_b32 v64, v68, v52 offset0:32 offset1:64
	ds_write2_b32 v64, v69, v53 offset0:164 offset1:196
	v_add_u32_e32 v52, 0x1400, v1
	v_lshl_add_u64 v[2:3], v[2:3], 0, v[4:5]
	v_lshlrev_b32_e32 v4, 4, v80
	ds_write2_b32 v52, v70, v54 offset0:40 offset1:72
	ds_write2_b32 v52, v71, v55 offset0:172 offset1:204
	v_add_u32_e32 v53, 0x2000, v1
	v_add_u32_e32 v54, 0x2400, v1
	v_and_b32_e32 v12, 48, v4
	v_mov_b32_e32 v13, v0
	ds_write2_b32 v53, v72, v56 offset0:64 offset1:96
	ds_write2_b32 v53, v73, v57 offset0:196 offset1:228
	ds_write2_b32 v54, v74, v58 offset0:72 offset1:104
	ds_write2_b32 v54, v75, v59 offset0:204 offset1:236
	v_add_u32_e32 v55, 0x3000, v1
	v_add_u32_e32 v56, 0x3200, v1
	v_add_u32_e32 v57, 0x3400, v1
	v_add_u32_e32 v58, 0x3600, v1
	v_lshl_add_u64 v[2:3], v[2:3], 0, v[12:13]
	ds_write2_b32 v55, v76, v60 offset0:96 offset1:128
	ds_write2_b32 v56, v77, v61 offset0:100 offset1:132
	ds_write2_b32 v57, v78, v62 offset0:104 offset1:136
	ds_write2_b32 v58, v79, v63 offset0:108 offset1:140
	s_waitcnt lgkmcnt(0)
	s_barrier
	global_load_dwordx4 v[4:7], v[2:3], off
	v_lshlrev_b32_e32 v48, 2, v8
	v_mad_u64_u32 v[8:9], s[2:3], v9, s13, v[48:49]
	v_add_u32_e32 v14, 0x100, v80
	ds_read_b128 v[60:63], v8
	ds_read_b128 v[66:69], v8 offset:16
	v_ashrrev_i32_e32 v59, 4, v14
	v_ashrrev_i32_e32 v14, 3, v14
	v_and_b32_e32 v50, 64, v14
	v_add_u32_e32 v14, s0, v14
	v_and_or_b32 v9, v59, 31, v50
	v_ashrrev_i32_e32 v50, 7, v14
	v_ashrrev_i32_e32 v51, 31, v50
	v_lshlrev_b64 v[50:51], 18, v[50:51]
	v_mov_b32_e32 v15, v0
	v_lshlrev_b32_e32 v14, 6, v9
	v_lshl_add_u64 v[50:51], v[10:11], 0, v[50:51]
	s_waitcnt vmcnt(0)
	v_lshlrev_b32_e32 v70, 16, v4
	v_and_b32_e32 v71, 0xffff0000, v4
	v_lshlrev_b32_e32 v4, 16, v5
	v_and_b32_e32 v5, 0xffff0000, v5
	v_lshlrev_b32_e32 v72, 16, v6
	v_and_b32_e32 v73, 0xffff0000, v6
	v_lshlrev_b32_e32 v6, 16, v7
	v_and_b32_e32 v7, 0xffff0000, v7
	s_waitcnt lgkmcnt(1)
	v_pk_add_f32 v[60:61], v[60:61], v[70:71]
	v_pk_add_f32 v[62:63], v[62:63], v[4:5]
	s_waitcnt lgkmcnt(0)
	v_pk_add_f32 v[66:67], v[66:67], v[72:73]
	v_pk_add_f32 v[68:69], v[68:69], v[6:7]
	v_cvt_pk_bf16_f32 v4, v60, v61
	v_cvt_pk_bf16_f32 v5, v62, v63
	v_cvt_pk_bf16_f32 v6, v66, v67
	v_cvt_pk_bf16_f32 v7, v68, v69
	global_store_dwordx4 v[2:3], v[4:7], off
	s_nop 1
	v_lshl_add_u64 v[4:5], v[50:51], 0, v[14:15]
	v_lshl_add_u64 v[4:5], v[4:5], 0, v[12:13]
	global_load_dwordx4 v[60:63], v[4:5], off
	v_add_u32_e32 v6, 0x200, v80
	v_ashrrev_i32_e32 v9, 4, v6
	v_ashrrev_i32_e32 v6, 3, v6
	v_and_b32_e32 v50, 64, v6
	v_add_u32_e32 v6, s0, v6
	v_mad_u64_u32 v[14:15], s[2:3], v59, s13, v[48:49]
	v_and_or_b32 v15, v9, 31, v50
	v_ashrrev_i32_e32 v50, 7, v6
	ds_read_b128 v[66:69], v14
	ds_read_b128 v[70:73], v14 offset:16
	v_ashrrev_i32_e32 v51, 31, v50
	v_lshlrev_b64 v[50:51], 18, v[50:51]
	v_mov_b32_e32 v7, v0
	v_lshlrev_b32_e32 v6, 6, v15
	v_lshl_add_u64 v[50:51], v[10:11], 0, v[50:51]
	v_lshl_add_u64 v[6:7], v[50:51], 0, v[6:7]
	v_lshl_add_u64 v[6:7], v[6:7], 0, v[12:13]
	v_add_u32_e32 v15, 0x300, v80
	v_ashrrev_i32_e32 v59, 4, v15
	v_ashrrev_i32_e32 v15, 3, v15
	v_and_b32_e32 v65, 64, v15
	v_add_u32_e32 v15, s0, v15
	s_waitcnt vmcnt(0)
	v_lshlrev_b32_e32 v50, 16, v60
	v_and_b32_e32 v51, 0xffff0000, v60
	v_lshlrev_b32_e32 v60, 16, v61
	v_and_b32_e32 v61, 0xffff0000, v61
	v_lshlrev_b32_e32 v74, 16, v62
	v_and_b32_e32 v75, 0xffff0000, v62
	v_lshlrev_b32_e32 v62, 16, v63
	v_and_b32_e32 v63, 0xffff0000, v63
	s_waitcnt lgkmcnt(1)
	v_pk_add_f32 v[50:51], v[66:67], v[50:51]
	v_pk_add_f32 v[66:67], v[68:69], v[60:61]
	s_waitcnt lgkmcnt(0)
	v_pk_add_f32 v[68:69], v[70:71], v[74:75]
	v_pk_add_f32 v[70:71], v[72:73], v[62:63]
	v_cvt_pk_bf16_f32 v60, v50, v51
	v_cvt_pk_bf16_f32 v61, v66, v67
	v_cvt_pk_bf16_f32 v62, v68, v69
	v_cvt_pk_bf16_f32 v63, v70, v71
	global_store_dwordx4 v[4:5], v[60:63], off
	global_load_dwordx4 v[60:63], v[6:7], off
	v_ashrrev_i32_e32 v66, 7, v15
	v_mad_u64_u32 v[50:51], s[0:1], v9, s13, v[48:49]
	v_ashrrev_i32_e32 v67, 31, v66
	v_lshlrev_b64 v[76:77], 18, v[66:67]
	ds_read_b128 v[66:69], v50
	ds_read_b128 v[70:73], v50 offset:16
	v_and_or_b32 v9, v59, 31, v65
	v_mov_b32_e32 v75, v0
	v_lshlrev_b32_e32 v74, 6, v9
	v_lshl_add_u64 v[10:11], v[10:11], 0, v[76:77]
	v_lshl_add_u64 v[10:11], v[10:11], 0, v[74:75]
	v_lshl_add_u64 v[10:11], v[10:11], 0, v[12:13]
	s_waitcnt vmcnt(0)
	v_lshlrev_b32_e32 v12, 16, v60
	v_and_b32_e32 v13, 0xffff0000, v60
	v_lshlrev_b32_e32 v60, 16, v61
	v_and_b32_e32 v61, 0xffff0000, v61
	v_lshlrev_b32_e32 v74, 16, v62
	v_and_b32_e32 v75, 0xffff0000, v62
	v_lshlrev_b32_e32 v62, 16, v63
	v_and_b32_e32 v63, 0xffff0000, v63
	s_waitcnt lgkmcnt(1)
	v_pk_add_f32 v[12:13], v[66:67], v[12:13]
	v_pk_add_f32 v[66:67], v[68:69], v[60:61]
	s_waitcnt lgkmcnt(0)
	v_pk_add_f32 v[68:69], v[70:71], v[74:75]
	v_pk_add_f32 v[70:71], v[72:73], v[62:63]
	v_cvt_pk_bf16_f32 v60, v12, v13
	v_cvt_pk_bf16_f32 v61, v66, v67
	v_cvt_pk_bf16_f32 v62, v68, v69
	v_cvt_pk_bf16_f32 v63, v70, v71
	global_store_dwordx4 v[6:7], v[60:63], off
	global_load_dwordx4 v[60:63], v[10:11], off
	v_mad_u64_u32 v[12:13], s[0:1], v59, s13, v[48:49]
	ds_read_b128 v[66:69], v12
	ds_read_b128 v[70:73], v12 offset:16
	s_waitcnt vmcnt(0)
	v_lshlrev_b32_e32 v74, 16, v60
	v_and_b32_e32 v75, 0xffff0000, v60
	v_lshlrev_b32_e32 v60, 16, v61
	v_and_b32_e32 v61, 0xffff0000, v61
	v_lshlrev_b32_e32 v76, 16, v62
	v_and_b32_e32 v77, 0xffff0000, v62
	v_lshlrev_b32_e32 v62, 16, v63
	v_and_b32_e32 v63, 0xffff0000, v63
	s_waitcnt lgkmcnt(1)
	v_pk_add_f32 v[66:67], v[66:67], v[74:75]
	v_pk_add_f32 v[68:69], v[68:69], v[60:61]
	s_waitcnt lgkmcnt(0)
	v_pk_add_f32 v[70:71], v[70:71], v[76:77]
	v_pk_add_f32 v[72:73], v[72:73], v[62:63]
	v_cvt_pk_bf16_f32 v60, v66, v67
	v_cvt_pk_bf16_f32 v61, v68, v69
	v_cvt_pk_bf16_f32 v62, v70, v71
	v_cvt_pk_bf16_f32 v63, v72, v73
	global_store_dwordx4 v[10:11], v[60:63], off
	s_barrier
	ds_write2_b32 v1, v32, v16 offset1:32
	ds_write2_b32 v1, v33, v17 offset0:132 offset1:164
	ds_write2_b32 v49, v34, v18 offset0:8 offset1:40
	ds_write2_b32 v49, v35, v19 offset0:140 offset1:172
	ds_write2_b32 v64, v36, v20 offset0:32 offset1:64
	ds_write2_b32 v64, v37, v21 offset0:164 offset1:196
	ds_write2_b32 v52, v38, v22 offset0:40 offset1:72
	ds_write2_b32 v52, v39, v23 offset0:172 offset1:204
	ds_write2_b32 v53, v40, v24 offset0:64 offset1:96
	ds_write2_b32 v53, v41, v25 offset0:196 offset1:228
	ds_write2_b32 v54, v42, v26 offset0:72 offset1:104
	ds_write2_b32 v54, v43, v27 offset0:204 offset1:236
	ds_write2_b32 v55, v44, v28 offset0:96 offset1:128
	ds_write2_b32 v56, v45, v29 offset0:100 offset1:132
	ds_write2_b32 v57, v46, v30 offset0:104 offset1:136
	ds_write2_b32 v58, v47, v31 offset0:108 offset1:140
	s_waitcnt lgkmcnt(0)
	s_barrier
	global_load_dwordx4 v[16:19], v[2:3], off offset:2048
	ds_read_b128 v[20:23], v8
	ds_read_b128 v[24:27], v8 offset:16
	s_waitcnt vmcnt(0)
	v_lshlrev_b32_e32 v8, 16, v16
	v_and_b32_e32 v9, 0xffff0000, v16
	v_lshlrev_b32_e32 v16, 16, v17
	v_and_b32_e32 v17, 0xffff0000, v17
	v_lshlrev_b32_e32 v28, 16, v18
	v_and_b32_e32 v29, 0xffff0000, v18
	v_lshlrev_b32_e32 v18, 16, v19
	v_and_b32_e32 v19, 0xffff0000, v19
	s_waitcnt lgkmcnt(1)
	v_pk_add_f32 v[8:9], v[20:21], v[8:9]
	v_pk_add_f32 v[20:21], v[22:23], v[16:17]
	s_waitcnt lgkmcnt(0)
	v_pk_add_f32 v[22:23], v[24:25], v[28:29]
	v_pk_add_f32 v[24:25], v[26:27], v[18:19]
	v_cvt_pk_bf16_f32 v16, v8, v9
	v_cvt_pk_bf16_f32 v17, v20, v21
	v_cvt_pk_bf16_f32 v18, v22, v23
	v_cvt_pk_bf16_f32 v19, v24, v25
	global_store_dwordx4 v[2:3], v[16:19], off offset:2048
	global_load_dwordx4 v[16:19], v[4:5], off offset:2048
	ds_read_b128 v[20:23], v14
	ds_read_b128 v[24:27], v14 offset:16
	s_waitcnt vmcnt(0)
	v_lshlrev_b32_e32 v2, 16, v16
	v_and_b32_e32 v3, 0xffff0000, v16
	v_lshlrev_b32_e32 v8, 16, v17
	v_and_b32_e32 v9, 0xffff0000, v17
	v_lshlrev_b32_e32 v14, 16, v18
	v_and_b32_e32 v15, 0xffff0000, v18
	v_lshlrev_b32_e32 v16, 16, v19
	v_and_b32_e32 v17, 0xffff0000, v19
	s_waitcnt lgkmcnt(1)
	v_pk_add_f32 v[2:3], v[20:21], v[2:3]
	v_pk_add_f32 v[8:9], v[22:23], v[8:9]
	s_waitcnt lgkmcnt(0)
	v_pk_add_f32 v[18:19], v[24:25], v[14:15]
	v_pk_add_f32 v[20:21], v[26:27], v[16:17]
	v_cvt_pk_bf16_f32 v14, v2, v3
	v_cvt_pk_bf16_f32 v15, v8, v9
	v_cvt_pk_bf16_f32 v16, v18, v19
	v_cvt_pk_bf16_f32 v17, v20, v21
	global_store_dwordx4 v[4:5], v[14:17], off offset:2048
	global_load_dwordx4 v[2:5], v[6:7], off offset:2048
	ds_read_b128 v[14:17], v50
	ds_read_b128 v[18:21], v50 offset:16
	s_waitcnt vmcnt(0)
	v_lshlrev_b32_e32 v8, 16, v2
	v_and_b32_e32 v9, 0xffff0000, v2
	v_lshlrev_b32_e32 v2, 16, v3
	v_and_b32_e32 v3, 0xffff0000, v3
	v_lshlrev_b32_e32 v22, 16, v4
	v_and_b32_e32 v23, 0xffff0000, v4
	v_lshlrev_b32_e32 v4, 16, v5
	v_and_b32_e32 v5, 0xffff0000, v5
	s_waitcnt lgkmcnt(1)
	v_pk_add_f32 v[8:9], v[14:15], v[8:9]
	v_pk_add_f32 v[14:15], v[16:17], v[2:3]
	s_waitcnt lgkmcnt(0)
	v_pk_add_f32 v[16:17], v[18:19], v[22:23]
	v_pk_add_f32 v[18:19], v[20:21], v[4:5]
	v_cvt_pk_bf16_f32 v2, v8, v9
	v_cvt_pk_bf16_f32 v3, v14, v15
	v_cvt_pk_bf16_f32 v4, v16, v17
	v_cvt_pk_bf16_f32 v5, v18, v19
	global_store_dwordx4 v[6:7], v[2:5], off offset:2048
	global_load_dwordx4 v[2:5], v[10:11], off offset:2048
	ds_read_b128 v[6:9], v12
	ds_read_b128 v[12:15], v12 offset:16
	s_waitcnt vmcnt(0)
	v_lshlrev_b32_e32 v16, 16, v2
	v_and_b32_e32 v17, 0xffff0000, v2
	v_lshlrev_b32_e32 v2, 16, v3
	v_and_b32_e32 v3, 0xffff0000, v3
	v_lshlrev_b32_e32 v18, 16, v4
	v_and_b32_e32 v19, 0xffff0000, v4
	v_lshlrev_b32_e32 v4, 16, v5
	v_and_b32_e32 v5, 0xffff0000, v5
	s_waitcnt lgkmcnt(1)
	v_pk_add_f32 v[6:7], v[6:7], v[16:17]
	v_pk_add_f32 v[8:9], v[8:9], v[2:3]
	s_waitcnt lgkmcnt(0)
	v_pk_add_f32 v[12:13], v[12:13], v[18:19]
	v_pk_add_f32 v[14:15], v[14:15], v[4:5]
	v_cvt_pk_bf16_f32 v2, v6, v7
	v_cvt_pk_bf16_f32 v3, v8, v9
	v_cvt_pk_bf16_f32 v4, v12, v13
	v_cvt_pk_bf16_f32 v5, v14, v15
	global_store_dwordx4 v[10:11], v[2:5], off offset:2048
	s_cmp_eq_u32 s32, 0
	s_cbranch_scc1 .Lg4a_pass2
	s_add_i32 s8, s8, s56
	s_cmp_lt_u32 s8, s57
	s_cbranch_scc1 .Lg4a_hdr
	s_branch .LBB0_637
.Lg4a_pass2:
	s_mov_b32 s32, 1
	v_mov_b32_e32 v64, v82
	v_mov_b32_e32 v65, v83
	v_mov_b32_e32 v66, v84
	v_mov_b32_e32 v67, v85
	v_mov_b32_e32 v68, v86
	v_mov_b32_e32 v69, v87
	v_mov_b32_e32 v70, v88
	v_mov_b32_e32 v71, v89
	v_mov_b32_e32 v72, v90
	v_mov_b32_e32 v73, v91
	v_mov_b32_e32 v74, v92
	v_mov_b32_e32 v75, v93
	v_mov_b32_e32 v76, v94
	v_mov_b32_e32 v77, v95
	v_mov_b32_e32 v78, v96
	v_mov_b32_e32 v79, v97
	v_mov_b32_e32 v48, v98
	v_mov_b32_e32 v49, v99
	v_mov_b32_e32 v50, v100
	v_mov_b32_e32 v51, v101
	v_mov_b32_e32 v52, v102
	v_mov_b32_e32 v53, v103
	v_mov_b32_e32 v54, v104
	v_mov_b32_e32 v55, v105
	v_mov_b32_e32 v56, v106
	v_mov_b32_e32 v57, v107
	v_mov_b32_e32 v58, v108
	v_mov_b32_e32 v59, v109
	v_mov_b32_e32 v60, v110
	v_mov_b32_e32 v61, v111
	v_mov_b32_e32 v62, v112
	v_mov_b32_e32 v63, v113
	v_mov_b32_e32 v32, v114
	v_mov_b32_e32 v33, v115
	v_mov_b32_e32 v34, v116
	v_mov_b32_e32 v35, v117
	v_mov_b32_e32 v36, v118
	v_mov_b32_e32 v37, v119
	v_mov_b32_e32 v38, v120
	v_mov_b32_e32 v39, v121
	v_mov_b32_e32 v40, v122
	v_mov_b32_e32 v41, v123
	v_mov_b32_e32 v42, v124
	v_mov_b32_e32 v43, v125
	v_mov_b32_e32 v44, v126
	v_mov_b32_e32 v45, v127
	v_mov_b32_e32 v46, v128
	v_mov_b32_e32 v47, v129
	v_mov_b32_e32 v16, v130
	v_mov_b32_e32 v17, v131
	v_mov_b32_e32 v18, v132
	v_mov_b32_e32 v19, v133
	v_mov_b32_e32 v20, v134
	v_mov_b32_e32 v21, v135
	v_mov_b32_e32 v22, v136
	v_mov_b32_e32 v23, v137
	v_mov_b32_e32 v24, v138
	v_mov_b32_e32 v25, v139
	v_mov_b32_e32 v26, v140
	v_mov_b32_e32 v27, v141
	v_mov_b32_e32 v28, v142
	v_mov_b32_e32 v29, v143
	v_mov_b32_e32 v30, v150
	v_mov_b32_e32 v31, v151
	s_mov_b32 s14, s30
	s_add_i32 s15, s31, 1
	s_waitcnt lgkmcnt(0)
	s_barrier
	s_branch .Lg4a_epi
.Lg4a_hdr:
	s_cmp_ge_u32 s8, 128
	s_cbranch_scc1 .Lg4a_lastgrp
	s_mul_hi_u32 s0, s8, 0x4000000
	s_mul_i32 s1, s0, 64
	s_sub_i32 s1, s8, s1
	s_lshr_b32 s4, s1, 4
	s_and_b32 s3, s1, 15
	s_lshl4_add_u32 s3, s0, s3
	s_branch .Lg4a_cont
.Lg4a_lastgrp:
	s_sub_u32 s1, s8, 128
	s_mul_hi_u32 s0, s1, 0x40000000
	s_mul_i32 s4, s0, 4
	s_sub_i32 s4, s1, s4
	s_add_u32 s3, s0, 32
.Lg4a_cont:
	s_lshl3_add_u32 s30, s3, s33
	s_lshl_b32 s31, s4, 1
	s_mul_i32 s0, s30, 0xb0000
	s_add_u32 s22, s46, s0
	s_addc_u32 s23, s47, 0
	s_mul_i32 s0, s31, 0xb0000
	s_add_u32 s0, s0, 0x1880000
	s_add_u32 s24, s48, s0
	s_addc_u32 s25, s49, 0
	s_add_u32 s26, s24, 0xb0000
	s_addc_u32 s27, s25, 0
	s_waitcnt vmcnt(0) lgkmcnt(0)
	s_barrier
	s_add_u32 m0, s28, 0x0
	s_nop 0
	global_load_lds_dwordx4 v157, s[22:23]
	global_load_lds_dwordx4 v157, s[22:23] offset:1024
	s_add_u32 s22, s22, 0x2000
	s_addc_u32 s23, s23, 0
	s_add_u32 m0, s28, 0x2000
	s_nop 0
	global_load_lds_dwordx4 v157, s[24:25]
	global_load_lds_dwordx4 v157, s[24:25] offset:1024
	s_add_u32 s24, s24, 0x2000
	s_addc_u32 s25, s25, 0
	s_add_u32 m0, s28, 0x4000
	s_nop 0
	global_load_lds_dwordx4 v157, s[26:27]
	global_load_lds_dwordx4 v157, s[26:27] offset:1024
	s_add_u32 s26, s26, 0x2000
	s_addc_u32 s27, s27, 0
	s_waitcnt vmcnt(0)
	s_barrier
	s_add_u32 m0, s28, 0x6000
	s_nop 0
	global_load_lds_dwordx4 v157, s[22:23]
	global_load_lds_dwordx4 v157, s[22:23] offset:1024
	s_add_u32 s22, s22, 0x2000
	s_addc_u32 s23, s23, 0
	s_add_u32 m0, s28, 0x8000
	s_nop 0
	global_load_lds_dwordx4 v157, s[24:25]
	global_load_lds_dwordx4 v157, s[24:25] offset:1024
	s_add_u32 s24, s24, 0x2000
	s_addc_u32 s25, s25, 0
	s_add_u32 m0, s28, 0xa400
	s_nop 0
	global_load_lds_dwordx4 v157, s[26:27]
	global_load_lds_dwordx4 v157, s[26:27] offset:1024
	s_add_u32 s26, s26, 0x2000
	s_addc_u32 s27, s27, 0
	ds_read_b128 v[130:133], v81 offset:0
	ds_read_b128 v[138:141], v146 offset:8192
	ds_read_b128 v[150:153], v146 offset:10240
	ds_read_b128 v[160:163], v146 offset:16384
	ds_read_b128 v[164:167], v146 offset:18432
	ds_read_b128 v[134:137], v81 offset:2048
	s_waitcnt lgkmcnt(4)
	v_mfma_f32_32x32x16_bf16 v[64:79], v[130:133], v[138:141], 0
	s_waitcnt lgkmcnt(3)
	v_mfma_f32_32x32x16_bf16 v[48:63], v[130:133], v[150:153], 0
	s_waitcnt lgkmcnt(2)
	v_mfma_f32_32x32x16_bf16 v[82:97], v[130:133], v[160:163], 0
	s_waitcnt lgkmcnt(1)
	v_mfma_f32_32x32x16_bf16 v[98:113], v[130:133], v[164:167], 0
	ds_read_b128 v[130:133], v145 offset:0
	s_waitcnt lgkmcnt(1)
	v_mfma_f32_32x32x16_bf16 v[0:15], v[134:137], v[164:167], 0
	ds_read_b128 v[164:167], v147 offset:18432
	v_mfma_f32_32x32x16_bf16 v[114:129], v[134:137], v[160:163], 0
	ds_read_b128 v[160:163], v147 offset:16384
	v_mfma_f32_32x32x16_bf16 v[16:31], v[134:137], v[150:153], 0
	ds_read_b128 v[150:153], v147 offset:10240
	v_mfma_f32_32x32x16_bf16 v[32:47], v[134:137], v[138:141], 0
	ds_read_b128 v[138:141], v147 offset:8192
	ds_read_b128 v[134:137], v145 offset:2048
	s_waitcnt lgkmcnt(4)
	v_mfma_f32_32x32x16_bf16 v[98:113], v[130:133], v[164:167], v[98:113]
	s_waitcnt lgkmcnt(3)
	v_mfma_f32_32x32x16_bf16 v[82:97], v[130:133], v[160:163], v[82:97]
	s_waitcnt lgkmcnt(2)
	v_mfma_f32_32x32x16_bf16 v[48:63], v[130:133], v[150:153], v[48:63]
	s_waitcnt lgkmcnt(1)
	v_mfma_f32_32x32x16_bf16 v[64:79], v[130:133], v[138:141], v[64:79]
	s_waitcnt vmcnt(0) lgkmcnt(0)
	s_barrier
	ds_read_b128 v[130:133], v81 offset:24576
	s_add_u32 m0, s28, 0x0
	s_nop 0
	global_load_lds_dwordx4 v157, s[22:23]
	global_load_lds_dwordx4 v157, s[22:23] offset:1024
	s_add_u32 s22, s22, 0x2000
	s_addc_u32 s23, s23, 0
	v_mfma_f32_32x32x16_bf16 v[32:47], v[134:137], v[138:141], v[32:47]
	ds_read_b128 v[138:141], v146 offset:32768
	s_add_u32 m0, s28, 0x2000
	s_nop 0
	global_load_lds_dwordx4 v157, s[24:25]
	global_load_lds_dwordx4 v157, s[24:25] offset:1024
	s_add_u32 s24, s24, 0x2000
	s_addc_u32 s25, s25, 0
	v_mfma_f32_32x32x16_bf16 v[16:31], v[134:137], v[150:153], v[16:31]
	ds_read_b128 v[150:153], v146 offset:34816
	s_add_u32 m0, s28, 0x4000
	s_nop 0
	global_load_lds_dwordx4 v157, s[26:27]
	global_load_lds_dwordx4 v157, s[26:27] offset:1024
	s_add_u32 s26, s26, 0x2000
	s_addc_u32 s27, s27, 0
	v_mfma_f32_32x32x16_bf16 v[114:129], v[134:137], v[160:163], v[114:129]
	ds_read_b128 v[160:163], v146 offset:41984
	v_mfma_f32_32x32x16_bf16 v[0:15], v[134:137], v[164:167], v[0:15]
	ds_read_b128 v[164:167], v146 offset:44032
	ds_read_b128 v[134:137], v81 offset:26624
	s_waitcnt lgkmcnt(4)
	v_mfma_f32_32x32x16_bf16 v[64:79], v[130:133], v[138:141], v[64:79]
	s_waitcnt lgkmcnt(3)
	v_mfma_f32_32x32x16_bf16 v[48:63], v[130:133], v[150:153], v[48:63]
	s_waitcnt lgkmcnt(2)
	v_mfma_f32_32x32x16_bf16 v[82:97], v[130:133], v[160:163], v[82:97]
	s_waitcnt lgkmcnt(1)
	v_mfma_f32_32x32x16_bf16 v[98:113], v[130:133], v[164:167], v[98:113]
	ds_read_b128 v[130:133], v145 offset:24576
	s_waitcnt lgkmcnt(1)
	v_mfma_f32_32x32x16_bf16 v[0:15], v[134:137], v[164:167], v[0:15]
	ds_read_b128 v[164:167], v147 offset:44032
	v_mfma_f32_32x32x16_bf16 v[114:129], v[134:137], v[160:163], v[114:129]
	ds_read_b128 v[160:163], v147 offset:41984
	v_mfma_f32_32x32x16_bf16 v[16:31], v[134:137], v[150:153], v[16:31]
	ds_read_b128 v[150:153], v147 offset:34816
	v_mfma_f32_32x32x16_bf16 v[32:47], v[134:137], v[138:141], v[32:47]
	ds_read_b128 v[138:141], v147 offset:32768
	ds_read_b128 v[134:137], v145 offset:26624
	s_waitcnt lgkmcnt(4)
	v_mfma_f32_32x32x16_bf16 v[98:113], v[130:133], v[164:167], v[98:113]
	s_waitcnt lgkmcnt(3)
	v_mfma_f32_32x32x16_bf16 v[82:97], v[130:133], v[160:163], v[82:97]
	s_waitcnt lgkmcnt(2)
	v_mfma_f32_32x32x16_bf16 v[48:63], v[130:133], v[150:153], v[48:63]
	s_waitcnt lgkmcnt(1)
	v_mfma_f32_32x32x16_bf16 v[64:79], v[130:133], v[138:141], v[64:79]
	s_waitcnt vmcnt(0) lgkmcnt(0)
	s_barrier
	ds_read_b128 v[130:133], v81 offset:0
	s_add_u32 m0, s28, 0x6000
	s_nop 0
	global_load_lds_dwordx4 v157, s[22:23]
	global_load_lds_dwordx4 v157, s[22:23] offset:1024
	s_add_u32 s22, s22, 0x2000
	s_addc_u32 s23, s23, 0
	v_mfma_f32_32x32x16_bf16 v[32:47], v[134:137], v[138:141], v[32:47]
	ds_read_b128 v[138:141], v146 offset:8192
	s_add_u32 m0, s28, 0x8000
	s_nop 0
	global_load_lds_dwordx4 v157, s[24:25]
	global_load_lds_dwordx4 v157, s[24:25] offset:1024
	s_add_u32 s24, s24, 0x2000
	s_addc_u32 s25, s25, 0
	v_mfma_f32_32x32x16_bf16 v[16:31], v[134:137], v[150:153], v[16:31]
	ds_read_b128 v[150:153], v146 offset:10240
	s_add_u32 m0, s28, 0xa400
	s_nop 0
	global_load_lds_dwordx4 v157, s[26:27]
	global_load_lds_dwordx4 v157, s[26:27] offset:1024
	s_add_u32 s26, s26, 0x2000
	s_addc_u32 s27, s27, 0
	v_mfma_f32_32x32x16_bf16 v[114:129], v[134:137], v[160:163], v[114:129]
	ds_read_b128 v[160:163], v146 offset:16384
	v_mfma_f32_32x32x16_bf16 v[0:15], v[134:137], v[164:167], v[0:15]
	ds_read_b128 v[164:167], v146 offset:18432
	ds_read_b128 v[134:137], v81 offset:2048
	s_mov_b32 s29, 42
.Lg4a_kloop:
	s_waitcnt lgkmcnt(4)
	v_mfma_f32_32x32x16_bf16 v[64:79], v[130:133], v[138:141], v[64:79]
	s_waitcnt lgkmcnt(3)
	v_mfma_f32_32x32x16_bf16 v[48:63], v[130:133], v[150:153], v[48:63]
	s_waitcnt lgkmcnt(2)
	v_mfma_f32_32x32x16_bf16 v[82:97], v[130:133], v[160:163], v[82:97]
	s_waitcnt lgkmcnt(1)
	v_mfma_f32_32x32x16_bf16 v[98:113], v[130:133], v[164:167], v[98:113]
	ds_read_b128 v[130:133], v145 offset:0
	s_waitcnt lgkmcnt(1)
	v_mfma_f32_32x32x16_bf16 v[0:15], v[134:137], v[164:167], v[0:15]
	ds_read_b128 v[164:167], v147 offset:18432
	v_mfma_f32_32x32x16_bf16 v[114:129], v[134:137], v[160:163], v[114:129]
	ds_read_b128 v[160:163], v147 offset:16384
	v_mfma_f32_32x32x16_bf16 v[16:31], v[134:137], v[150:153], v[16:31]
	ds_read_b128 v[150:153], v147 offset:10240
	v_mfma_f32_32x32x16_bf16 v[32:47], v[134:137], v[138:141], v[32:47]
	ds_read_b128 v[138:141], v147 offset:8192
	ds_read_b128 v[134:137], v145 offset:2048
	s_waitcnt lgkmcnt(4)
	v_mfma_f32_32x32x16_bf16 v[98:113], v[130:133], v[164:167], v[98:113]
	s_waitcnt lgkmcnt(3)
	v_mfma_f32_32x32x16_bf16 v[82:97], v[130:133], v[160:163], v[82:97]
	s_waitcnt lgkmcnt(2)
	v_mfma_f32_32x32x16_bf16 v[48:63], v[130:133], v[150:153], v[48:63]
	s_waitcnt lgkmcnt(1)
	v_mfma_f32_32x32x16_bf16 v[64:79], v[130:133], v[138:141], v[64:79]
	s_waitcnt vmcnt(0) lgkmcnt(0)
	s_barrier
	ds_read_b128 v[130:133], v81 offset:24576
	s_add_u32 m0, s28, 0x0
	s_nop 0
	global_load_lds_dwordx4 v157, s[22:23]
	global_load_lds_dwordx4 v157, s[22:23] offset:1024
	s_add_u32 s22, s22, 0x2000
	s_addc_u32 s23, s23, 0
	v_mfma_f32_32x32x16_bf16 v[32:47], v[134:137], v[138:141], v[32:47]
	ds_read_b128 v[138:141], v146 offset:32768
	s_add_u32 m0, s28, 0x2000
	s_nop 0
	global_load_lds_dwordx4 v157, s[24:25]
	global_load_lds_dwordx4 v157, s[24:25] offset:1024
	s_add_u32 s24, s24, 0x2000
	s_addc_u32 s25, s25, 0
	v_mfma_f32_32x32x16_bf16 v[16:31], v[134:137], v[150:153], v[16:31]
	ds_read_b128 v[150:153], v146 offset:34816
	s_add_u32 m0, s28, 0x4000
	s_nop 0
	global_load_lds_dwordx4 v157, s[26:27]
	global_load_lds_dwordx4 v157, s[26:27] offset:1024
	s_add_u32 s26, s26, 0x2000
	s_addc_u32 s27, s27, 0
	v_mfma_f32_32x32x16_bf16 v[114:129], v[134:137], v[160:163], v[114:129]
	ds_read_b128 v[160:163], v146 offset:41984
	v_mfma_f32_32x32x16_bf16 v[0:15], v[134:137], v[164:167], v[0:15]
	ds_read_b128 v[164:167], v146 offset:44032
	ds_read_b128 v[134:137], v81 offset:26624
	s_waitcnt lgkmcnt(4)
	v_mfma_f32_32x32x16_bf16 v[64:79], v[130:133], v[138:141], v[64:79]
	s_waitcnt lgkmcnt(3)
	v_mfma_f32_32x32x16_bf16 v[48:63], v[130:133], v[150:153], v[48:63]
	s_waitcnt lgkmcnt(2)
	v_mfma_f32_32x32x16_bf16 v[82:97], v[130:133], v[160:163], v[82:97]
	s_waitcnt lgkmcnt(1)
	v_mfma_f32_32x32x16_bf16 v[98:113], v[130:133], v[164:167], v[98:113]
	ds_read_b128 v[130:133], v145 offset:24576
	s_waitcnt lgkmcnt(1)
	v_mfma_f32_32x32x16_bf16 v[0:15], v[134:137], v[164:167], v[0:15]
	ds_read_b128 v[164:167], v147 offset:44032
	v_mfma_f32_32x32x16_bf16 v[114:129], v[134:137], v[160:163], v[114:129]
	ds_read_b128 v[160:163], v147 offset:41984
	v_mfma_f32_32x32x16_bf16 v[16:31], v[134:137], v[150:153], v[16:31]
	ds_read_b128 v[150:153], v147 offset:34816
	v_mfma_f32_32x32x16_bf16 v[32:47], v[134:137], v[138:141], v[32:47]
	ds_read_b128 v[138:141], v147 offset:32768
	ds_read_b128 v[134:137], v145 offset:26624
	s_waitcnt lgkmcnt(4)
	v_mfma_f32_32x32x16_bf16 v[98:113], v[130:133], v[164:167], v[98:113]
	s_waitcnt lgkmcnt(3)
	v_mfma_f32_32x32x16_bf16 v[82:97], v[130:133], v[160:163], v[82:97]
	s_waitcnt lgkmcnt(2)
	v_mfma_f32_32x32x16_bf16 v[48:63], v[130:133], v[150:153], v[48:63]
	s_waitcnt lgkmcnt(1)
	v_mfma_f32_32x32x16_bf16 v[64:79], v[130:133], v[138:141], v[64:79]
	s_waitcnt vmcnt(0) lgkmcnt(0)
	s_barrier
	ds_read_b128 v[130:133], v81 offset:0
	s_add_u32 m0, s28, 0x6000
	s_nop 0
	global_load_lds_dwordx4 v157, s[22:23]
	global_load_lds_dwordx4 v157, s[22:23] offset:1024
	s_add_u32 s22, s22, 0x2000
	s_addc_u32 s23, s23, 0
	v_mfma_f32_32x32x16_bf16 v[32:47], v[134:137], v[138:141], v[32:47]
	ds_read_b128 v[138:141], v146 offset:8192
	s_add_u32 m0, s28, 0x8000
	s_nop 0
	global_load_lds_dwordx4 v157, s[24:25]
	global_load_lds_dwordx4 v157, s[24:25] offset:1024
	s_add_u32 s24, s24, 0x2000
	s_addc_u32 s25, s25, 0
	v_mfma_f32_32x32x16_bf16 v[16:31], v[134:137], v[150:153], v[16:31]
	ds_read_b128 v[150:153], v146 offset:10240
	s_add_u32 m0, s28, 0xa400
	s_nop 0
	global_load_lds_dwordx4 v157, s[26:27]
	global_load_lds_dwordx4 v157, s[26:27] offset:1024
	s_add_u32 s26, s26, 0x2000
	s_addc_u32 s27, s27, 0
	v_mfma_f32_32x32x16_bf16 v[114:129], v[134:137], v[160:163], v[114:129]
	ds_read_b128 v[160:163], v146 offset:16384
	v_mfma_f32_32x32x16_bf16 v[0:15], v[134:137], v[164:167], v[0:15]
	ds_read_b128 v[164:167], v146 offset:18432
	ds_read_b128 v[134:137], v81 offset:2048
	s_sub_u32 s29, s29, 1
	s_cmp_lg_u32 s29, 0
	s_cbranch_scc1 .Lg4a_kloop
	s_waitcnt lgkmcnt(4)
	v_mfma_f32_32x32x16_bf16 v[64:79], v[130:133], v[138:141], v[64:79]
	s_waitcnt lgkmcnt(3)
	v_mfma_f32_32x32x16_bf16 v[48:63], v[130:133], v[150:153], v[48:63]
	s_waitcnt lgkmcnt(2)
	v_mfma_f32_32x32x16_bf16 v[82:97], v[130:133], v[160:163], v[82:97]
	s_waitcnt lgkmcnt(1)
	v_mfma_f32_32x32x16_bf16 v[98:113], v[130:133], v[164:167], v[98:113]
	ds_read_b128 v[130:133], v145 offset:0
	s_waitcnt lgkmcnt(1)
	v_mfma_f32_32x32x16_bf16 v[0:15], v[134:137], v[164:167], v[0:15]
	ds_read_b128 v[164:167], v147 offset:18432
	v_mfma_f32_32x32x16_bf16 v[114:129], v[134:137], v[160:163], v[114:129]
	ds_read_b128 v[160:163], v147 offset:16384
	v_mfma_f32_32x32x16_bf16 v[16:31], v[134:137], v[150:153], v[16:31]
	ds_read_b128 v[150:153], v147 offset:10240
	v_mfma_f32_32x32x16_bf16 v[32:47], v[134:137], v[138:141], v[32:47]
	ds_read_b128 v[138:141], v147 offset:8192
	ds_read_b128 v[134:137], v145 offset:2048
	s_waitcnt lgkmcnt(4)
	v_mfma_f32_32x32x16_bf16 v[98:113], v[130:133], v[164:167], v[98:113]
	s_waitcnt lgkmcnt(3)
	v_mfma_f32_32x32x16_bf16 v[82:97], v[130:133], v[160:163], v[82:97]
	s_waitcnt lgkmcnt(2)
	v_mfma_f32_32x32x16_bf16 v[48:63], v[130:133], v[150:153], v[48:63]
	s_waitcnt lgkmcnt(1)
	v_mfma_f32_32x32x16_bf16 v[64:79], v[130:133], v[138:141], v[64:79]
	s_waitcnt vmcnt(0) lgkmcnt(0)
	s_barrier
	ds_read_b128 v[130:133], v81 offset:24576
	v_mfma_f32_32x32x16_bf16 v[32:47], v[134:137], v[138:141], v[32:47]
	ds_read_b128 v[138:141], v146 offset:32768
	v_mfma_f32_32x32x16_bf16 v[16:31], v[134:137], v[150:153], v[16:31]
	ds_read_b128 v[150:153], v146 offset:34816
	v_mfma_f32_32x32x16_bf16 v[114:129], v[134:137], v[160:163], v[114:129]
	ds_read_b128 v[160:163], v146 offset:41984
	v_mfma_f32_32x32x16_bf16 v[0:15], v[134:137], v[164:167], v[0:15]
	ds_read_b128 v[164:167], v146 offset:44032
	ds_read_b128 v[134:137], v81 offset:26624
	s_waitcnt lgkmcnt(4)
	v_mfma_f32_32x32x16_bf16 v[64:79], v[130:133], v[138:141], v[64:79]
	s_waitcnt lgkmcnt(3)
	v_mfma_f32_32x32x16_bf16 v[48:63], v[130:133], v[150:153], v[48:63]
	s_waitcnt lgkmcnt(2)
	v_mfma_f32_32x32x16_bf16 v[82:97], v[130:133], v[160:163], v[82:97]
	s_waitcnt lgkmcnt(1)
	v_mfma_f32_32x32x16_bf16 v[98:113], v[130:133], v[164:167], v[98:113]
	ds_read_b128 v[130:133], v145 offset:24576
	s_waitcnt lgkmcnt(1)
	v_mfma_f32_32x32x16_bf16 v[0:15], v[134:137], v[164:167], v[0:15]
	ds_read_b128 v[164:167], v147 offset:44032
	v_mfma_f32_32x32x16_bf16 v[114:129], v[134:137], v[160:163], v[114:129]
	ds_read_b128 v[160:163], v147 offset:41984
	v_mfma_f32_32x32x16_bf16 v[16:31], v[134:137], v[150:153], v[16:31]
	ds_read_b128 v[150:153], v147 offset:34816
	v_mfma_f32_32x32x16_bf16 v[32:47], v[134:137], v[138:141], v[32:47]
	ds_read_b128 v[138:141], v147 offset:32768
	ds_read_b128 v[134:137], v145 offset:26624
	s_waitcnt lgkmcnt(4)
	v_mfma_f32_32x32x16_bf16 v[98:113], v[130:133], v[164:167], v[98:113]
	s_waitcnt lgkmcnt(3)
	v_mfma_f32_32x32x16_bf16 v[82:97], v[130:133], v[160:163], v[82:97]
	s_waitcnt lgkmcnt(2)
	v_mfma_f32_32x32x16_bf16 v[48:63], v[130:133], v[150:153], v[48:63]
	s_waitcnt lgkmcnt(1)
	v_mfma_f32_32x32x16_bf16 v[64:79], v[130:133], v[138:141], v[64:79]
	s_waitcnt lgkmcnt(0)
	v_mfma_f32_32x32x16_bf16 v[32:47], v[134:137], v[138:141], v[32:47]
	v_mfma_f32_32x32x16_bf16 v[16:31], v[134:137], v[150:153], v[16:31]
	v_mfma_f32_32x32x16_bf16 v[114:129], v[134:137], v[160:163], v[114:129]
	v_mfma_f32_32x32x16_bf16 v[0:15], v[134:137], v[164:167], v[0:15]
	s_nop 7
	s_nop 7
	v_mov_b32_e32 v130, v0
	v_mov_b32_e32 v131, v1
	v_mov_b32_e32 v132, v2
	v_mov_b32_e32 v133, v3
	v_mov_b32_e32 v134, v4
	v_mov_b32_e32 v135, v5
	v_mov_b32_e32 v136, v6
	v_mov_b32_e32 v137, v7
	v_mov_b32_e32 v138, v8
	v_mov_b32_e32 v139, v9
	v_mov_b32_e32 v140, v10
	v_mov_b32_e32 v141, v11
	v_mov_b32_e32 v142, v12
	v_mov_b32_e32 v143, v13
	v_mov_b32_e32 v150, v14
	v_mov_b32_e32 v151, v15
	s_mov_b32 s32, 0
	s_mov_b32 s14, s30
	s_mov_b32 s15, s31
	s_waitcnt lgkmcnt(0)
	s_barrier
	s_branch .Lg4a_epi

.Lg3b_cont:
	s_lshl3_add_u32 s26, s6, s29
	s_lshl_b32 s27, s7, 1
	s_mul_i32 s1, s26, 0x40000
	s_add_u32 s18, s44, s1
	s_addc_u32 s19, s45, 0
	s_mul_i32 s1, s27, 0x40000
	s_add_u32 s1, s1, 0xd80000
	s_add_u32 s20, s48, s1
	s_addc_u32 s21, s49, 0
	s_add_u32 s22, s20, 0x40000
	s_addc_u32 s23, s21, 0
	s_waitcnt vmcnt(0) lgkmcnt(0)
	s_barrier
	s_add_u32 m0, s24, 0x0
	s_nop 0
	global_load_lds_dwordx4 v164, s[18:19]
	global_load_lds_dwordx4 v164, s[18:19] offset:1024
	s_add_u32 s18, s18, 0x2000
	s_addc_u32 s19, s19, 0
	s_add_u32 m0, s24, 0x2000
	s_nop 0
	global_load_lds_dwordx4 v164, s[20:21]
	global_load_lds_dwordx4 v164, s[20:21] offset:1024
	s_add_u32 s20, s20, 0x2000
	s_addc_u32 s21, s21, 0
	s_add_u32 m0, s24, 0x4000
	s_nop 0
	global_load_lds_dwordx4 v164, s[22:23]
	global_load_lds_dwordx4 v164, s[22:23] offset:1024
	s_add_u32 s22, s22, 0x2000
	s_addc_u32 s23, s23, 0
	s_waitcnt vmcnt(0)
	s_barrier
	s_add_u32 m0, s24, 0x6000
	s_nop 0
	global_load_lds_dwordx4 v164, s[18:19]
	global_load_lds_dwordx4 v164, s[18:19] offset:1024
	s_add_u32 s18, s18, 0x2000
	s_addc_u32 s19, s19, 0
	s_add_u32 m0, s24, 0x8000
	s_nop 0
	global_load_lds_dwordx4 v164, s[20:21]
	global_load_lds_dwordx4 v164, s[20:21] offset:1024
	s_add_u32 s20, s20, 0x2000
	s_addc_u32 s21, s21, 0
	s_add_u32 m0, s24, 0xa400
	s_nop 0
	global_load_lds_dwordx4 v164, s[22:23]
	global_load_lds_dwordx4 v164, s[22:23] offset:1024
	s_add_u32 s22, s22, 0x2000
	s_addc_u32 s23, s23, 0
	ds_read_b128 v[64:67], v160 offset:0
	ds_read_b128 v[90:93], v162 offset:8192
	ds_read_b128 v[142:145], v162 offset:10240
	ds_read_b128 v[150:153], v162 offset:16384
	ds_read_b128 v[154:157], v162 offset:18432
	ds_read_b128 v[68:71], v160 offset:2048
	s_waitcnt lgkmcnt(4)
	v_mfma_f32_32x32x16_bf16 v[48:63], v[64:67], v[90:93], 0
	s_waitcnt lgkmcnt(3)
	v_mfma_f32_32x32x16_bf16 v[32:47], v[64:67], v[142:145], 0
	s_waitcnt lgkmcnt(2)
	v_mfma_f32_32x32x16_bf16 v[94:109], v[64:67], v[150:153], 0
	s_waitcnt lgkmcnt(1)
	v_mfma_f32_32x32x16_bf16 v[110:125], v[64:67], v[154:157], 0
	ds_read_b128 v[64:67], v161 offset:0
	s_waitcnt lgkmcnt(1)
	v_mfma_f32_32x32x16_bf16 v[74:89], v[68:71], v[154:157], 0
	ds_read_b128 v[154:157], v163 offset:18432
	v_mfma_f32_32x32x16_bf16 v[126:141], v[68:71], v[150:153], 0
	ds_read_b128 v[150:153], v163 offset:16384
	v_mfma_f32_32x32x16_bf16 v[0:15], v[68:71], v[142:145], 0
	ds_read_b128 v[142:145], v163 offset:10240
	v_mfma_f32_32x32x16_bf16 v[16:31], v[68:71], v[90:93], 0
	ds_read_b128 v[90:93], v163 offset:8192
	ds_read_b128 v[68:71], v161 offset:2048
	s_waitcnt lgkmcnt(4)
	v_mfma_f32_32x32x16_bf16 v[110:125], v[64:67], v[154:157], v[110:125]
	s_waitcnt lgkmcnt(3)
	v_mfma_f32_32x32x16_bf16 v[94:109], v[64:67], v[150:153], v[94:109]
	s_waitcnt lgkmcnt(2)
	v_mfma_f32_32x32x16_bf16 v[32:47], v[64:67], v[142:145], v[32:47]
	s_waitcnt lgkmcnt(1)
	v_mfma_f32_32x32x16_bf16 v[48:63], v[64:67], v[90:93], v[48:63]
	s_waitcnt vmcnt(0) lgkmcnt(0)
	s_barrier
	ds_read_b128 v[64:67], v160 offset:24576
	s_add_u32 m0, s24, 0x0
	s_nop 0
	global_load_lds_dwordx4 v164, s[18:19]
	global_load_lds_dwordx4 v164, s[18:19] offset:1024
	s_add_u32 s18, s18, 0x2000
	s_addc_u32 s19, s19, 0
	v_mfma_f32_32x32x16_bf16 v[16:31], v[68:71], v[90:93], v[16:31]
	ds_read_b128 v[90:93], v162 offset:32768
	s_add_u32 m0, s24, 0x2000
	s_nop 0
	global_load_lds_dwordx4 v164, s[20:21]
	global_load_lds_dwordx4 v164, s[20:21] offset:1024
	s_add_u32 s20, s20, 0x2000
	s_addc_u32 s21, s21, 0
	v_mfma_f32_32x32x16_bf16 v[0:15], v[68:71], v[142:145], v[0:15]
	ds_read_b128 v[142:145], v162 offset:34816
	s_add_u32 m0, s24, 0x4000
	s_nop 0
	global_load_lds_dwordx4 v164, s[22:23]
	global_load_lds_dwordx4 v164, s[22:23] offset:1024
	s_add_u32 s22, s22, 0x2000
	s_addc_u32 s23, s23, 0
	v_mfma_f32_32x32x16_bf16 v[126:141], v[68:71], v[150:153], v[126:141]
	ds_read_b128 v[150:153], v162 offset:41984
	v_mfma_f32_32x32x16_bf16 v[74:89], v[68:71], v[154:157], v[74:89]
	ds_read_b128 v[154:157], v162 offset:44032
	ds_read_b128 v[68:71], v160 offset:26624
	s_waitcnt lgkmcnt(4)
	v_mfma_f32_32x32x16_bf16 v[48:63], v[64:67], v[90:93], v[48:63]
	s_waitcnt lgkmcnt(3)
	v_mfma_f32_32x32x16_bf16 v[32:47], v[64:67], v[142:145], v[32:47]
	s_waitcnt lgkmcnt(2)
	v_mfma_f32_32x32x16_bf16 v[94:109], v[64:67], v[150:153], v[94:109]
	s_waitcnt lgkmcnt(1)
	v_mfma_f32_32x32x16_bf16 v[110:125], v[64:67], v[154:157], v[110:125]
	ds_read_b128 v[64:67], v161 offset:24576
	s_waitcnt lgkmcnt(1)
	v_mfma_f32_32x32x16_bf16 v[74:89], v[68:71], v[154:157], v[74:89]
	ds_read_b128 v[154:157], v163 offset:44032
	v_mfma_f32_32x32x16_bf16 v[126:141], v[68:71], v[150:153], v[126:141]
	ds_read_b128 v[150:153], v163 offset:41984
	v_mfma_f32_32x32x16_bf16 v[0:15], v[68:71], v[142:145], v[0:15]
	ds_read_b128 v[142:145], v163 offset:34816
	v_mfma_f32_32x32x16_bf16 v[16:31], v[68:71], v[90:93], v[16:31]
	ds_read_b128 v[90:93], v163 offset:32768
	ds_read_b128 v[68:71], v161 offset:26624
	s_waitcnt lgkmcnt(4)
	v_mfma_f32_32x32x16_bf16 v[110:125], v[64:67], v[154:157], v[110:125]
	s_waitcnt lgkmcnt(3)
	v_mfma_f32_32x32x16_bf16 v[94:109], v[64:67], v[150:153], v[94:109]
	s_waitcnt lgkmcnt(2)
	v_mfma_f32_32x32x16_bf16 v[32:47], v[64:67], v[142:145], v[32:47]
	s_waitcnt lgkmcnt(1)
	v_mfma_f32_32x32x16_bf16 v[48:63], v[64:67], v[90:93], v[48:63]
	s_waitcnt vmcnt(0) lgkmcnt(0)
	s_barrier
	ds_read_b128 v[64:67], v160 offset:0
	s_add_u32 m0, s24, 0x6000
	s_nop 0
	global_load_lds_dwordx4 v164, s[18:19]
	global_load_lds_dwordx4 v164, s[18:19] offset:1024
	s_add_u32 s18, s18, 0x2000
	s_addc_u32 s19, s19, 0
	v_mfma_f32_32x32x16_bf16 v[16:31], v[68:71], v[90:93], v[16:31]
	ds_read_b128 v[90:93], v162 offset:8192
	s_add_u32 m0, s24, 0x8000
	s_nop 0
	global_load_lds_dwordx4 v164, s[20:21]
	global_load_lds_dwordx4 v164, s[20:21] offset:1024
	s_add_u32 s20, s20, 0x2000
	s_addc_u32 s21, s21, 0
	v_mfma_f32_32x32x16_bf16 v[0:15], v[68:71], v[142:145], v[0:15]
	ds_read_b128 v[142:145], v162 offset:10240
	s_add_u32 m0, s24, 0xa400
	s_nop 0
	global_load_lds_dwordx4 v164, s[22:23]
	global_load_lds_dwordx4 v164, s[22:23] offset:1024
	s_add_u32 s22, s22, 0x2000
	s_addc_u32 s23, s23, 0
	v_mfma_f32_32x32x16_bf16 v[126:141], v[68:71], v[150:153], v[126:141]
	ds_read_b128 v[150:153], v162 offset:16384
	v_mfma_f32_32x32x16_bf16 v[74:89], v[68:71], v[154:157], v[74:89]
	ds_read_b128 v[154:157], v162 offset:18432
	ds_read_b128 v[68:71], v160 offset:2048
	s_mov_b32 s25, 14

.LBB0_1316:
	s_or_b64 exec, exec, s[2:3]
	v_mov_b32_e32 v144, v148
	s_mov_b32 s8, s55
	s_waitcnt lgkmcnt(0)
	s_barrier
	s_mov_b32 s9, s94
	s_cmpk_gt_i32 s8, 0x827
	s_cbranch_scc1 .LBB0_1339
	s_waitcnt vmcnt(0)
	v_ashrrev_i32_e32 v8, 2, v144
	v_lshlrev_b32_e32 v0, 5, v8
	v_ashrrev_i32_e32 v1, 31, v0
	v_lshlrev_b64 v[2:3], 1, v[0:1]
	v_lshlrev_b32_e32 v0, 4, v144
	v_and_b32_e32 v6, 48, v0
	v_mov_b32_e32 v0, 0
	v_readlane_b32 s0, v158, 26
	v_lshl_add_u64 v[4:5], s[46:47], 0, v[2:3]
	v_mov_b32_e32 v7, v0
	v_readlane_b32 s1, v158, 27
	v_lshl_add_u64 v[132:133], v[4:5], 0, v[6:7]
	v_mov_b32_e32 v145, 0xb0000
	v_lshl_add_u64 v[4:5], s[0:1], 0, v[2:3]
	v_lshl_add_u64 v[134:135], v[4:5], 0, v[6:7]
	v_lshrrev_b32_e32 v4, 1, v144
	v_and_b32_e32 v7, 31, v144
	s_mov_b32 s1, 0xfffffc0
	s_movk_i32 s0, 0x50
	v_and_b32_e32 v5, 16, v4
	v_and_or_b32 v4, v4, s1, v7
	v_and_b32_e32 v7, 0x5f, v144
	v_mul_lo_u32 v1, v8, s0
	v_mul_lo_u32 v4, v4, s0
	v_mul_u32_u24_e32 v7, 0x50, v7
	v_or_b32_e32 v2, v2, v6
	v_lshl_add_u64 v[136:137], s[48:49], 0, v[2:3]
	s_movk_i32 s10, 0x2000
	s_movk_i32 s11, 0x4000
	s_movk_i32 s12, 0x5000
	v_add_u32_e32 v146, v1, v6
	v_add_u32_e32 v147, v5, v4
	v_add_u32_e32 v150, v5, v7
	s_movk_i32 s13, 0x7000
	s_mov_b32 s14, 0x1887000
	s_movk_i32 s15, 0x210
	v_and_b32_e32 v142, 63, v148
	v_lshrrev_b32_e32 v143, 6, v148
	v_and_b32_e32 v154, 31, v142
	v_lshlrev_b32_e32 v154, 6, v154
	v_lshrrev_b32_e32 v155, 5, v142
	v_bfe_u32 v156, v142, 2, 2
	v_xor_b32_e32 v155, v155, v156
	v_lshl_add_u32 v154, v155, 4, v154
	v_lshrrev_b32_e32 v155, 1, v143
	v_lshl_add_u32 v81, v155, 12, v154
	v_and_b32_e32 v155, 1, v143
	v_lshl_add_u32 v146, v155, 12, v154
	v_xor_b32_e32 v145, 32, v81
	v_xor_b32_e32 v147, 32, v146
	v_lshrrev_b32_e32 v154, 2, v142
	v_lshlrev_b32_e32 v154, 6, v154
	v_and_b32_e32 v155, 3, v142
	v_bfe_u32 v156, v142, 4, 2
	v_xor_b32_e32 v155, v155, v156
	v_lshl_add_u32 v154, v155, 4, v154
	v_lshl_add_u32 v157, v143, 11, v154
	v_readfirstlane_b32 s28, v143
	s_lshl_b32 s28, s28, 11
	s_and_b32 s33, s8, 7
	s_lshr_b32 s8, s8, 3
	s_lshr_b32 s56, s9, 3
	s_sub_u32 s57, 268, s33
	s_lshr_b32 s57, s57, 3
	s_mul_i32 s57, s57, 4
	s_branch .Lg4b_hdr
.LBB0_1318:
.Lg4b_epi:
	v_mov_b32_e32 v0, 0
	s_waitcnt vmcnt(3)
	v_mov_b32_e32 v80, v144
	s_lshl_b32 s0, s16, 7
	v_lshlrev_b32_e32 v1, 3, v80
	v_lshrrev_b32_e32 v5, 2, v80
	s_waitcnt vmcnt(2)
	v_and_b32_e32 v8, 0x78, v1
	v_lshrrev_b32_e32 v4, 3, v80
	v_and_b32_e32 v5, 0xfffffe0, v5
	v_lshl_or_b32 v1, s17, 7, v8
	v_and_or_b32 v4, v4, 4, v5
	v_ashrrev_i32_e32 v2, 5, v1
	v_and_b32_e32 v1, 0x5f, v80
	v_mul_lo_u32 v4, v4, s15
	v_lshl_add_u32 v1, v1, 2, v4
	v_ashrrev_i32_e32 v4, 3, v80
	v_and_b32_e32 v5, 64, v4
	v_add_u32_e32 v4, s0, v4
	v_ashrrev_i32_e32 v3, 31, v2
	v_ashrrev_i32_e32 v9, 4, v80
	v_ashrrev_i32_e32 v4, 7, v4
	v_lshlrev_b64 v[2:3], 13, v[2:3]
	v_and_or_b32 v6, v9, 31, v5
	v_ashrrev_i32_e32 v5, 31, v4
	s_waitcnt vmcnt(1)
	v_lshl_add_u64 v[10:11], s[44:45], 0, v[2:3]
	v_lshlrev_b64 v[2:3], 18, v[4:5]
	ds_write2_b32 v1, v64, v48 offset1:32
	ds_write2_b32 v1, v65, v49 offset0:132 offset1:164
	v_add_u32_e32 v49, 0x400, v1
	v_add_u32_e32 v64, 0x1000, v1
	v_lshl_add_u64 v[2:3], v[10:11], 0, v[2:3]
	v_lshlrev_b32_e32 v4, 6, v6
	v_mov_b32_e32 v5, v0
	ds_write2_b32 v49, v66, v50 offset0:8 offset1:40
	ds_write2_b32 v49, v67, v51 offset0:140 offset1:172
	ds_write2_b32 v64, v68, v52 offset0:32 offset1:64
	ds_write2_b32 v64, v69, v53 offset0:164 offset1:196
	v_add_u32_e32 v52, 0x1400, v1
	v_lshl_add_u64 v[2:3], v[2:3], 0, v[4:5]
	v_lshlrev_b32_e32 v4, 4, v80
	ds_write2_b32 v52, v70, v54 offset0:40 offset1:72
	ds_write2_b32 v52, v71, v55 offset0:172 offset1:204
	v_add_u32_e32 v53, 0x2000, v1
	v_add_u32_e32 v54, 0x2400, v1
	v_and_b32_e32 v12, 48, v4
	v_mov_b32_e32 v13, v0
	ds_write2_b32 v53, v72, v56 offset0:64 offset1:96
	ds_write2_b32 v53, v73, v57 offset0:196 offset1:228
	ds_write2_b32 v54, v74, v58 offset0:72 offset1:104
	ds_write2_b32 v54, v75, v59 offset0:204 offset1:236
	v_add_u32_e32 v55, 0x3000, v1
	v_add_u32_e32 v56, 0x3200, v1
	v_add_u32_e32 v57, 0x3400, v1
	v_add_u32_e32 v58, 0x3600, v1
	v_lshl_add_u64 v[2:3], v[2:3], 0, v[12:13]
	ds_write2_b32 v55, v76, v60 offset0:96 offset1:128
	ds_write2_b32 v56, v77, v61 offset0:100 offset1:132
	ds_write2_b32 v57, v78, v62 offset0:104 offset1:136
	ds_write2_b32 v58, v79, v63 offset0:108 offset1:140
	s_waitcnt lgkmcnt(0)
	s_barrier
	global_load_dwordx4 v[4:7], v[2:3], off
	v_lshlrev_b32_e32 v48, 2, v8
	v_mad_u64_u32 v[8:9], s[2:3], v9, s15, v[48:49]
	v_add_u32_e32 v14, 0x100, v80
	ds_read_b128 v[60:63], v8
	ds_read_b128 v[66:69], v8 offset:16
	v_ashrrev_i32_e32 v59, 4, v14
	v_ashrrev_i32_e32 v14, 3, v14
	v_and_b32_e32 v50, 64, v14
	v_add_u32_e32 v14, s0, v14
	v_and_or_b32 v9, v59, 31, v50
	v_ashrrev_i32_e32 v50, 7, v14
	v_ashrrev_i32_e32 v51, 31, v50
	v_lshlrev_b64 v[50:51], 18, v[50:51]
	v_mov_b32_e32 v15, v0
	v_lshlrev_b32_e32 v14, 6, v9
	v_lshl_add_u64 v[50:51], v[10:11], 0, v[50:51]
	s_waitcnt vmcnt(0)
	v_lshlrev_b32_e32 v70, 16, v4
	v_and_b32_e32 v71, 0xffff0000, v4
	v_lshlrev_b32_e32 v4, 16, v5
	v_and_b32_e32 v5, 0xffff0000, v5
	v_lshlrev_b32_e32 v72, 16, v6
	v_and_b32_e32 v73, 0xffff0000, v6
	v_lshlrev_b32_e32 v6, 16, v7
	v_and_b32_e32 v7, 0xffff0000, v7
	s_waitcnt lgkmcnt(1)
	v_pk_add_f32 v[60:61], v[60:61], v[70:71]
	v_pk_add_f32 v[62:63], v[62:63], v[4:5]
	s_waitcnt lgkmcnt(0)
	v_pk_add_f32 v[66:67], v[66:67], v[72:73]
	v_pk_add_f32 v[68:69], v[68:69], v[6:7]
	v_cvt_pk_bf16_f32 v4, v60, v61
	v_cvt_pk_bf16_f32 v5, v62, v63
	v_cvt_pk_bf16_f32 v6, v66, v67
	v_cvt_pk_bf16_f32 v7, v68, v69
	global_store_dwordx4 v[2:3], v[4:7], off
	s_nop 1
	v_lshl_add_u64 v[4:5], v[50:51], 0, v[14:15]
	v_lshl_add_u64 v[4:5], v[4:5], 0, v[12:13]
	global_load_dwordx4 v[60:63], v[4:5], off
	v_add_u32_e32 v6, 0x200, v80
	v_ashrrev_i32_e32 v9, 4, v6
	v_ashrrev_i32_e32 v6, 3, v6
	v_and_b32_e32 v50, 64, v6
	v_add_u32_e32 v6, s0, v6
	v_mad_u64_u32 v[14:15], s[2:3], v59, s15, v[48:49]
	v_and_or_b32 v15, v9, 31, v50
	v_ashrrev_i32_e32 v50, 7, v6
	ds_read_b128 v[66:69], v14
	ds_read_b128 v[70:73], v14 offset:16
	v_ashrrev_i32_e32 v51, 31, v50
	v_lshlrev_b64 v[50:51], 18, v[50:51]
	v_mov_b32_e32 v7, v0
	v_lshlrev_b32_e32 v6, 6, v15
	v_lshl_add_u64 v[50:51], v[10:11], 0, v[50:51]
	v_lshl_add_u64 v[6:7], v[50:51], 0, v[6:7]
	v_lshl_add_u64 v[6:7], v[6:7], 0, v[12:13]
	v_add_u32_e32 v15, 0x300, v80
	v_ashrrev_i32_e32 v59, 4, v15
	v_ashrrev_i32_e32 v15, 3, v15
	v_and_b32_e32 v65, 64, v15
	v_add_u32_e32 v15, s0, v15
	s_waitcnt vmcnt(0)
	v_lshlrev_b32_e32 v50, 16, v60
	v_and_b32_e32 v51, 0xffff0000, v60
	v_lshlrev_b32_e32 v60, 16, v61
	v_and_b32_e32 v61, 0xffff0000, v61
	v_lshlrev_b32_e32 v74, 16, v62
	v_and_b32_e32 v75, 0xffff0000, v62
	v_lshlrev_b32_e32 v62, 16, v63
	v_and_b32_e32 v63, 0xffff0000, v63
	s_waitcnt lgkmcnt(1)
	v_pk_add_f32 v[50:51], v[66:67], v[50:51]
	v_pk_add_f32 v[66:67], v[68:69], v[60:61]
	s_waitcnt lgkmcnt(0)
	v_pk_add_f32 v[68:69], v[70:71], v[74:75]
	v_pk_add_f32 v[70:71], v[72:73], v[62:63]
	v_cvt_pk_bf16_f32 v60, v50, v51
	v_cvt_pk_bf16_f32 v61, v66, v67
	v_cvt_pk_bf16_f32 v62, v68, v69
	v_cvt_pk_bf16_f32 v63, v70, v71
	global_store_dwordx4 v[4:5], v[60:63], off
	global_load_dwordx4 v[60:63], v[6:7], off
	v_ashrrev_i32_e32 v66, 7, v15
	v_mad_u64_u32 v[50:51], s[0:1], v9, s15, v[48:49]
	v_ashrrev_i32_e32 v67, 31, v66
	v_lshlrev_b64 v[76:77], 18, v[66:67]
	ds_read_b128 v[66:69], v50
	ds_read_b128 v[70:73], v50 offset:16
	v_and_or_b32 v9, v59, 31, v65
	v_mov_b32_e32 v75, v0
	v_lshlrev_b32_e32 v74, 6, v9
	v_lshl_add_u64 v[10:11], v[10:11], 0, v[76:77]
	v_lshl_add_u64 v[10:11], v[10:11], 0, v[74:75]
	v_lshl_add_u64 v[10:11], v[10:11], 0, v[12:13]
	s_waitcnt vmcnt(0)
	v_lshlrev_b32_e32 v12, 16, v60
	v_and_b32_e32 v13, 0xffff0000, v60
	v_lshlrev_b32_e32 v60, 16, v61
	v_and_b32_e32 v61, 0xffff0000, v61
	v_lshlrev_b32_e32 v74, 16, v62
	v_and_b32_e32 v75, 0xffff0000, v62
	v_lshlrev_b32_e32 v62, 16, v63
	v_and_b32_e32 v63, 0xffff0000, v63
	s_waitcnt lgkmcnt(1)
	v_pk_add_f32 v[12:13], v[66:67], v[12:13]
	v_pk_add_f32 v[66:67], v[68:69], v[60:61]
	s_waitcnt lgkmcnt(0)
	v_pk_add_f32 v[68:69], v[70:71], v[74:75]
	v_pk_add_f32 v[70:71], v[72:73], v[62:63]
	v_cvt_pk_bf16_f32 v60, v12, v13
	v_cvt_pk_bf16_f32 v61, v66, v67
	v_cvt_pk_bf16_f32 v62, v68, v69
	v_cvt_pk_bf16_f32 v63, v70, v71
	global_store_dwordx4 v[6:7], v[60:63], off
	global_load_dwordx4 v[60:63], v[10:11], off
	v_mad_u64_u32 v[12:13], s[0:1], v59, s15, v[48:49]
	ds_read_b128 v[66:69], v12
	ds_read_b128 v[70:73], v12 offset:16
	s_waitcnt vmcnt(0)
	v_lshlrev_b32_e32 v74, 16, v60
	v_and_b32_e32 v75, 0xffff0000, v60
	v_lshlrev_b32_e32 v60, 16, v61
	v_and_b32_e32 v61, 0xffff0000, v61
	v_lshlrev_b32_e32 v76, 16, v62
	v_and_b32_e32 v77, 0xffff0000, v62
	v_lshlrev_b32_e32 v62, 16, v63
	v_and_b32_e32 v63, 0xffff0000, v63
	s_waitcnt lgkmcnt(1)
	v_pk_add_f32 v[66:67], v[66:67], v[74:75]
	v_pk_add_f32 v[68:69], v[68:69], v[60:61]
	s_waitcnt lgkmcnt(0)
	v_pk_add_f32 v[70:71], v[70:71], v[76:77]
	v_pk_add_f32 v[72:73], v[72:73], v[62:63]
	v_cvt_pk_bf16_f32 v60, v66, v67
	v_cvt_pk_bf16_f32 v61, v68, v69
	v_cvt_pk_bf16_f32 v62, v70, v71
	v_cvt_pk_bf16_f32 v63, v72, v73
	global_store_dwordx4 v[10:11], v[60:63], off
	s_barrier
	ds_write2_b32 v1, v32, v16 offset1:32
	ds_write2_b32 v1, v33, v17 offset0:132 offset1:164
	ds_write2_b32 v49, v34, v18 offset0:8 offset1:40
	ds_write2_b32 v49, v35, v19 offset0:140 offset1:172
	ds_write2_b32 v64, v36, v20 offset0:32 offset1:64
	ds_write2_b32 v64, v37, v21 offset0:164 offset1:196
	ds_write2_b32 v52, v38, v22 offset0:40 offset1:72
	ds_write2_b32 v52, v39, v23 offset0:172 offset1:204
	ds_write2_b32 v53, v40, v24 offset0:64 offset1:96
	ds_write2_b32 v53, v41, v25 offset0:196 offset1:228
	ds_write2_b32 v54, v42, v26 offset0:72 offset1:104
	ds_write2_b32 v54, v43, v27 offset0:204 offset1:236
	ds_write2_b32 v55, v44, v28 offset0:96 offset1:128
	ds_write2_b32 v56, v45, v29 offset0:100 offset1:132
	ds_write2_b32 v57, v46, v30 offset0:104 offset1:136
	ds_write2_b32 v58, v47, v31 offset0:108 offset1:140
	s_waitcnt lgkmcnt(0)
	s_barrier
	global_load_dwordx4 v[16:19], v[2:3], off offset:2048
	ds_read_b128 v[20:23], v8
	ds_read_b128 v[24:27], v8 offset:16
	s_waitcnt vmcnt(0)
	v_lshlrev_b32_e32 v8, 16, v16
	v_and_b32_e32 v9, 0xffff0000, v16
	v_lshlrev_b32_e32 v16, 16, v17
	v_and_b32_e32 v17, 0xffff0000, v17
	v_lshlrev_b32_e32 v28, 16, v18
	v_and_b32_e32 v29, 0xffff0000, v18
	v_lshlrev_b32_e32 v18, 16, v19
	v_and_b32_e32 v19, 0xffff0000, v19
	s_waitcnt lgkmcnt(1)
	v_pk_add_f32 v[8:9], v[20:21], v[8:9]
	v_pk_add_f32 v[20:21], v[22:23], v[16:17]
	s_waitcnt lgkmcnt(0)
	v_pk_add_f32 v[22:23], v[24:25], v[28:29]
	v_pk_add_f32 v[24:25], v[26:27], v[18:19]
	v_cvt_pk_bf16_f32 v16, v8, v9
	v_cvt_pk_bf16_f32 v17, v20, v21
	v_cvt_pk_bf16_f32 v18, v22, v23
	v_cvt_pk_bf16_f32 v19, v24, v25
	global_store_dwordx4 v[2:3], v[16:19], off offset:2048
	global_load_dwordx4 v[16:19], v[4:5], off offset:2048
	ds_read_b128 v[20:23], v14
	ds_read_b128 v[24:27], v14 offset:16
	s_waitcnt vmcnt(0)
	v_lshlrev_b32_e32 v2, 16, v16
	v_and_b32_e32 v3, 0xffff0000, v16
	v_lshlrev_b32_e32 v8, 16, v17
	v_and_b32_e32 v9, 0xffff0000, v17
	v_lshlrev_b32_e32 v14, 16, v18
	v_and_b32_e32 v15, 0xffff0000, v18
	v_lshlrev_b32_e32 v16, 16, v19
	v_and_b32_e32 v17, 0xffff0000, v19
	s_waitcnt lgkmcnt(1)
	v_pk_add_f32 v[2:3], v[20:21], v[2:3]
	v_pk_add_f32 v[8:9], v[22:23], v[8:9]
	s_waitcnt lgkmcnt(0)
	v_pk_add_f32 v[18:19], v[24:25], v[14:15]
	v_pk_add_f32 v[20:21], v[26:27], v[16:17]
	v_cvt_pk_bf16_f32 v14, v2, v3
	v_cvt_pk_bf16_f32 v15, v8, v9
	v_cvt_pk_bf16_f32 v16, v18, v19
	v_cvt_pk_bf16_f32 v17, v20, v21
	global_store_dwordx4 v[4:5], v[14:17], off offset:2048
	global_load_dwordx4 v[2:5], v[6:7], off offset:2048
	ds_read_b128 v[14:17], v50
	ds_read_b128 v[18:21], v50 offset:16
	s_waitcnt vmcnt(0)
	v_lshlrev_b32_e32 v8, 16, v2
	v_and_b32_e32 v9, 0xffff0000, v2
	v_lshlrev_b32_e32 v2, 16, v3
	v_and_b32_e32 v3, 0xffff0000, v3
	v_lshlrev_b32_e32 v22, 16, v4
	v_and_b32_e32 v23, 0xffff0000, v4
	v_lshlrev_b32_e32 v4, 16, v5
	v_and_b32_e32 v5, 0xffff0000, v5
	s_waitcnt lgkmcnt(1)
	v_pk_add_f32 v[8:9], v[14:15], v[8:9]
	v_pk_add_f32 v[14:15], v[16:17], v[2:3]
	s_waitcnt lgkmcnt(0)
	v_pk_add_f32 v[16:17], v[18:19], v[22:23]
	v_pk_add_f32 v[18:19], v[20:21], v[4:5]
	v_cvt_pk_bf16_f32 v2, v8, v9
	v_cvt_pk_bf16_f32 v3, v14, v15
	v_cvt_pk_bf16_f32 v4, v16, v17
	v_cvt_pk_bf16_f32 v5, v18, v19
	global_store_dwordx4 v[6:7], v[2:5], off offset:2048
	global_load_dwordx4 v[2:5], v[10:11], off offset:2048
	ds_read_b128 v[6:9], v12
	ds_read_b128 v[12:15], v12 offset:16
	s_waitcnt vmcnt(0)
	v_lshlrev_b32_e32 v16, 16, v2
	v_and_b32_e32 v17, 0xffff0000, v2
	v_lshlrev_b32_e32 v2, 16, v3
	v_and_b32_e32 v3, 0xffff0000, v3
	v_lshlrev_b32_e32 v18, 16, v4
	v_and_b32_e32 v19, 0xffff0000, v4
	v_lshlrev_b32_e32 v4, 16, v5
	v_and_b32_e32 v5, 0xffff0000, v5
	s_waitcnt lgkmcnt(1)
	v_pk_add_f32 v[6:7], v[6:7], v[16:17]
	v_pk_add_f32 v[8:9], v[8:9], v[2:3]
	s_waitcnt lgkmcnt(0)
	v_pk_add_f32 v[12:13], v[12:13], v[18:19]
	v_pk_add_f32 v[14:15], v[14:15], v[4:5]
	v_cvt_pk_bf16_f32 v2, v6, v7
	v_cvt_pk_bf16_f32 v3, v8, v9
	v_cvt_pk_bf16_f32 v4, v12, v13
	v_cvt_pk_bf16_f32 v5, v14, v15
	global_store_dwordx4 v[10:11], v[2:5], off offset:2048
	s_cmp_eq_u32 s32, 0
	s_cbranch_scc1 .Lg4b_pass2
	s_add_i32 s8, s8, s56
	s_cmp_lt_u32 s8, s57
	s_cbranch_scc1 .Lg4b_hdr
	s_branch .LBB0_1339
.Lg4b_pass2:
	s_mov_b32 s32, 1
	v_mov_b32_e32 v64, v82
	v_mov_b32_e32 v65, v83
	v_mov_b32_e32 v66, v84
	v_mov_b32_e32 v67, v85
	v_mov_b32_e32 v68, v86
	v_mov_b32_e32 v69, v87
	v_mov_b32_e32 v70, v88
	v_mov_b32_e32 v71, v89
	v_mov_b32_e32 v72, v90
	v_mov_b32_e32 v73, v91
	v_mov_b32_e32 v74, v92
	v_mov_b32_e32 v75, v93
	v_mov_b32_e32 v76, v94
	v_mov_b32_e32 v77, v95
	v_mov_b32_e32 v78, v96
	v_mov_b32_e32 v79, v97
	v_mov_b32_e32 v48, v98
	v_mov_b32_e32 v49, v99
	v_mov_b32_e32 v50, v100
	v_mov_b32_e32 v51, v101
	v_mov_b32_e32 v52, v102
	v_mov_b32_e32 v53, v103
	v_mov_b32_e32 v54, v104
	v_mov_b32_e32 v55, v105
	v_mov_b32_e32 v56, v106
	v_mov_b32_e32 v57, v107
	v_mov_b32_e32 v58, v108
	v_mov_b32_e32 v59, v109
	v_mov_b32_e32 v60, v110
	v_mov_b32_e32 v61, v111
	v_mov_b32_e32 v62, v112
	v_mov_b32_e32 v63, v113
	v_mov_b32_e32 v32, v114
	v_mov_b32_e32 v33, v115
	v_mov_b32_e32 v34, v116
	v_mov_b32_e32 v35, v117
	v_mov_b32_e32 v36, v118
	v_mov_b32_e32 v37, v119
	v_mov_b32_e32 v38, v120
	v_mov_b32_e32 v39, v121
	v_mov_b32_e32 v40, v122
	v_mov_b32_e32 v41, v123
	v_mov_b32_e32 v42, v124
	v_mov_b32_e32 v43, v125
	v_mov_b32_e32 v44, v126
	v_mov_b32_e32 v45, v127
	v_mov_b32_e32 v46, v128
	v_mov_b32_e32 v47, v129
	v_mov_b32_e32 v16, v130
	v_mov_b32_e32 v17, v131
	v_mov_b32_e32 v18, v132
	v_mov_b32_e32 v19, v133
	v_mov_b32_e32 v20, v134
	v_mov_b32_e32 v21, v135
	v_mov_b32_e32 v22, v136
	v_mov_b32_e32 v23, v137
	v_mov_b32_e32 v24, v138
	v_mov_b32_e32 v25, v139
	v_mov_b32_e32 v26, v140
	v_mov_b32_e32 v27, v141
	v_mov_b32_e32 v28, v142
	v_mov_b32_e32 v29, v143
	v_mov_b32_e32 v30, v150
	v_mov_b32_e32 v31, v151
	s_mov_b32 s16, s30
	s_add_i32 s17, s31, 1
	s_waitcnt lgkmcnt(0)
	s_barrier
	s_branch .Lg4b_epi

.Lg4b_kloop:
	s_waitcnt lgkmcnt(4)
	v_mfma_f32_32x32x16_bf16 v[64:79], v[130:133], v[138:141], v[64:79]
	s_waitcnt lgkmcnt(3)
	v_mfma_f32_32x32x16_bf16 v[48:63], v[130:133], v[150:153], v[48:63]
	s_waitcnt lgkmcnt(2)
	v_mfma_f32_32x32x16_bf16 v[82:97], v[130:133], v[160:163], v[82:97]
	s_waitcnt lgkmcnt(1)
	v_mfma_f32_32x32x16_bf16 v[98:113], v[130:133], v[164:167], v[98:113]
	ds_read_b128 v[130:133], v145 offset:0
	s_waitcnt lgkmcnt(1)
	v_mfma_f32_32x32x16_bf16 v[0:15], v[134:137], v[164:167], v[0:15]
	ds_read_b128 v[164:167], v147 offset:18432
	v_mfma_f32_32x32x16_bf16 v[114:129], v[134:137], v[160:163], v[114:129]
	ds_read_b128 v[160:163], v147 offset:16384
	v_mfma_f32_32x32x16_bf16 v[16:31], v[134:137], v[150:153], v[16:31]
	ds_read_b128 v[150:153], v147 offset:10240
	v_mfma_f32_32x32x16_bf16 v[32:47], v[134:137], v[138:141], v[32:47]
	ds_read_b128 v[138:141], v147 offset:8192
	ds_read_b128 v[134:137], v145 offset:2048
	s_waitcnt lgkmcnt(4)
	v_mfma_f32_32x32x16_bf16 v[98:113], v[130:133], v[164:167], v[98:113]
	s_waitcnt lgkmcnt(3)
	v_mfma_f32_32x32x16_bf16 v[82:97], v[130:133], v[160:163], v[82:97]
	s_waitcnt lgkmcnt(2)
	v_mfma_f32_32x32x16_bf16 v[48:63], v[130:133], v[150:153], v[48:63]
	s_waitcnt lgkmcnt(1)
	v_mfma_f32_32x32x16_bf16 v[64:79], v[130:133], v[138:141], v[64:79]
	s_waitcnt vmcnt(0) lgkmcnt(0)
	s_barrier
	ds_read_b128 v[130:133], v81 offset:24576
	s_add_u32 m0, s28, 0x0
	s_nop 0
	global_load_lds_dwordx4 v157, s[22:23]
	global_load_lds_dwordx4 v157, s[22:23] offset:1024
	s_add_u32 s22, s22, 0x2000
	s_addc_u32 s23, s23, 0
	v_mfma_f32_32x32x16_bf16 v[32:47], v[134:137], v[138:141], v[32:47]
	ds_read_b128 v[138:141], v146 offset:32768
	s_add_u32 m0, s28, 0x2000
	s_nop 0
	global_load_lds_dwordx4 v157, s[24:25]
	global_load_lds_dwordx4 v157, s[24:25] offset:1024
	s_add_u32 s24, s24, 0x2000
	s_addc_u32 s25, s25, 0
	v_mfma_f32_32x32x16_bf16 v[16:31], v[134:137], v[150:153], v[16:31]
	ds_read_b128 v[150:153], v146 offset:34816
	s_add_u32 m0, s28, 0x4000
	s_nop 0
	global_load_lds_dwordx4 v157, s[26:27]
	global_load_lds_dwordx4 v157, s[26:27] offset:1024
	s_add_u32 s26, s26, 0x2000
	s_addc_u32 s27, s27, 0
	v_mfma_f32_32x32x16_bf16 v[114:129], v[134:137], v[160:163], v[114:129]
	ds_read_b128 v[160:163], v146 offset:41984
	v_mfma_f32_32x32x16_bf16 v[0:15], v[134:137], v[164:167], v[0:15]
	ds_read_b128 v[164:167], v146 offset:44032
	ds_read_b128 v[134:137], v81 offset:26624
	s_waitcnt lgkmcnt(4)
	v_mfma_f32_32x32x16_bf16 v[64:79], v[130:133], v[138:141], v[64:79]
	s_waitcnt lgkmcnt(3)
	v_mfma_f32_32x32x16_bf16 v[48:63], v[130:133], v[150:153], v[48:63]
	s_waitcnt lgkmcnt(2)
	v_mfma_f32_32x32x16_bf16 v[82:97], v[130:133], v[160:163], v[82:97]
	s_waitcnt lgkmcnt(1)
	v_mfma_f32_32x32x16_bf16 v[98:113], v[130:133], v[164:167], v[98:113]
	ds_read_b128 v[130:133], v145 offset:24576
	s_waitcnt lgkmcnt(1)
	v_mfma_f32_32x32x16_bf16 v[0:15], v[134:137], v[164:167], v[0:15]
	ds_read_b128 v[164:167], v147 offset:44032
	v_mfma_f32_32x32x16_bf16 v[114:129], v[134:137], v[160:163], v[114:129]
	ds_read_b128 v[160:163], v147 offset:41984
	v_mfma_f32_32x32x16_bf16 v[16:31], v[134:137], v[150:153], v[16:31]
	ds_read_b128 v[150:153], v147 offset:34816
	v_mfma_f32_32x32x16_bf16 v[32:47], v[134:137], v[138:141], v[32:47]
	ds_read_b128 v[138:141], v147 offset:32768
	ds_read_b128 v[134:137], v145 offset:26624
	s_waitcnt lgkmcnt(4)
	v_mfma_f32_32x32x16_bf16 v[98:113], v[130:133], v[164:167], v[98:113]
	s_waitcnt lgkmcnt(3)
	v_mfma_f32_32x32x16_bf16 v[82:97], v[130:133], v[160:163], v[82:97]
	s_waitcnt lgkmcnt(2)
	v_mfma_f32_32x32x16_bf16 v[48:63], v[130:133], v[150:153], v[48:63]
	s_waitcnt lgkmcnt(1)
	v_mfma_f32_32x32x16_bf16 v[64:79], v[130:133], v[138:141], v[64:79]
	s_waitcnt vmcnt(0) lgkmcnt(0)
	s_barrier
	ds_read_b128 v[130:133], v81 offset:0
	s_add_u32 m0, s28, 0x6000
	s_nop 0
	global_load_lds_dwordx4 v157, s[22:23]
	global_load_lds_dwordx4 v157, s[22:23] offset:1024
	s_add_u32 s22, s22, 0x2000
	s_addc_u32 s23, s23, 0
	v_mfma_f32_32x32x16_bf16 v[32:47], v[134:137], v[138:141], v[32:47]
	ds_read_b128 v[138:141], v146 offset:8192
	s_add_u32 m0, s28, 0x8000
	s_nop 0
	global_load_lds_dwordx4 v157, s[24:25]
	global_load_lds_dwordx4 v157, s[24:25] offset:1024
	s_add_u32 s24, s24, 0x2000
	s_addc_u32 s25, s25, 0
	v_mfma_f32_32x32x16_bf16 v[16:31], v[134:137], v[150:153], v[16:31]
	ds_read_b128 v[150:153], v146 offset:10240
	s_add_u32 m0, s28, 0xa400
	s_nop 0
	global_load_lds_dwordx4 v157, s[26:27]
	global_load_lds_dwordx4 v157, s[26:27] offset:1024
	s_add_u32 s26, s26, 0x2000
	s_addc_u32 s27, s27, 0
	v_mfma_f32_32x32x16_bf16 v[114:129], v[134:137], v[160:163], v[114:129]
	ds_read_b128 v[160:163], v146 offset:16384
	v_mfma_f32_32x32x16_bf16 v[0:15], v[134:137], v[164:167], v[0:15]
	ds_read_b128 v[164:167], v146 offset:18432
	ds_read_b128 v[134:137], v81 offset:2048
	s_sub_u32 s29, s29, 1
	s_cmp_lg_u32 s29, 0
	s_cbranch_scc1 .Lg4b_kloop
	s_waitcnt lgkmcnt(4)
	v_mfma_f32_32x32x16_bf16 v[64:79], v[130:133], v[138:141], v[64:79]
	s_waitcnt lgkmcnt(3)
	v_mfma_f32_32x32x16_bf16 v[48:63], v[130:133], v[150:153], v[48:63]
	s_waitcnt lgkmcnt(2)
	v_mfma_f32_32x32x16_bf16 v[82:97], v[130:133], v[160:163], v[82:97]
	s_waitcnt lgkmcnt(1)
	v_mfma_f32_32x32x16_bf16 v[98:113], v[130:133], v[164:167], v[98:113]
	ds_read_b128 v[130:133], v145 offset:0
	s_waitcnt lgkmcnt(1)
	v_mfma_f32_32x32x16_bf16 v[0:15], v[134:137], v[164:167], v[0:15]
	ds_read_b128 v[164:167], v147 offset:18432
	v_mfma_f32_32x32x16_bf16 v[114:129], v[134:137], v[160:163], v[114:129]
	ds_read_b128 v[160:163], v147 offset:16384
	v_mfma_f32_32x32x16_bf16 v[16:31], v[134:137], v[150:153], v[16:31]
	ds_read_b128 v[150:153], v147 offset:10240
	v_mfma_f32_32x32x16_bf16 v[32:47], v[134:137], v[138:141], v[32:47]
	ds_read_b128 v[138:141], v147 offset:8192
	ds_read_b128 v[134:137], v145 offset:2048
	s_waitcnt lgkmcnt(4)
	v_mfma_f32_32x32x16_bf16 v[98:113], v[130:133], v[164:167], v[98:113]
	s_waitcnt lgkmcnt(3)
	v_mfma_f32_32x32x16_bf16 v[82:97], v[130:133], v[160:163], v[82:97]
	s_waitcnt lgkmcnt(2)
	v_mfma_f32_32x32x16_bf16 v[48:63], v[130:133], v[150:153], v[48:63]
	s_waitcnt lgkmcnt(1)
	v_mfma_f32_32x32x16_bf16 v[64:79], v[130:133], v[138:141], v[64:79]
	s_waitcnt vmcnt(0) lgkmcnt(0)
	s_barrier
	ds_read_b128 v[130:133], v81 offset:24576
	v_mfma_f32_32x32x16_bf16 v[32:47], v[134:137], v[138:141], v[32:47]
	ds_read_b128 v[138:141], v146 offset:32768
	v_mfma_f32_32x32x16_bf16 v[16:31], v[134:137], v[150:153], v[16:31]
	ds_read_b128 v[150:153], v146 offset:34816
	v_mfma_f32_32x32x16_bf16 v[114:129], v[134:137], v[160:163], v[114:129]
	ds_read_b128 v[160:163], v146 offset:41984
	v_mfma_f32_32x32x16_bf16 v[0:15], v[134:137], v[164:167], v[0:15]
	ds_read_b128 v[164:167], v146 offset:44032
	ds_read_b128 v[134:137], v81 offset:26624
	s_waitcnt lgkmcnt(4)
	v_mfma_f32_32x32x16_bf16 v[64:79], v[130:133], v[138:141], v[64:79]
	s_waitcnt lgkmcnt(3)
	v_mfma_f32_32x32x16_bf16 v[48:63], v[130:133], v[150:153], v[48:63]
	s_waitcnt lgkmcnt(2)
	v_mfma_f32_32x32x16_bf16 v[82:97], v[130:133], v[160:163], v[82:97]
	s_waitcnt lgkmcnt(1)
	v_mfma_f32_32x32x16_bf16 v[98:113], v[130:133], v[164:167], v[98:113]
	ds_read_b128 v[130:133], v145 offset:24576
	s_waitcnt lgkmcnt(1)
	v_mfma_f32_32x32x16_bf16 v[0:15], v[134:137], v[164:167], v[0:15]
	ds_read_b128 v[164:167], v147 offset:44032
	v_mfma_f32_32x32x16_bf16 v[114:129], v[134:137], v[160:163], v[114:129]
	ds_read_b128 v[160:163], v147 offset:41984
	v_mfma_f32_32x32x16_bf16 v[16:31], v[134:137], v[150:153], v[16:31]
	ds_read_b128 v[150:153], v147 offset:34816
	v_mfma_f32_32x32x16_bf16 v[32:47], v[134:137], v[138:141], v[32:47]
	ds_read_b128 v[138:141], v147 offset:32768
	ds_read_b128 v[134:137], v145 offset:26624
	s_waitcnt lgkmcnt(4)
	v_mfma_f32_32x32x16_bf16 v[98:113], v[130:133], v[164:167], v[98:113]
	s_waitcnt lgkmcnt(3)
	v_mfma_f32_32x32x16_bf16 v[82:97], v[130:133], v[160:163], v[82:97]
	s_waitcnt lgkmcnt(2)
	v_mfma_f32_32x32x16_bf16 v[48:63], v[130:133], v[150:153], v[48:63]
	s_waitcnt lgkmcnt(1)
	v_mfma_f32_32x32x16_bf16 v[64:79], v[130:133], v[138:141], v[64:79]
	s_waitcnt lgkmcnt(0)
	v_mfma_f32_32x32x16_bf16 v[32:47], v[134:137], v[138:141], v[32:47]
	v_mfma_f32_32x32x16_bf16 v[16:31], v[134:137], v[150:153], v[16:31]
	v_mfma_f32_32x32x16_bf16 v[114:129], v[134:137], v[160:163], v[114:129]
	v_mfma_f32_32x32x16_bf16 v[0:15], v[134:137], v[164:167], v[0:15]
	s_nop 7
	s_nop 7
	v_mov_b32_e32 v130, v0
	v_mov_b32_e32 v131, v1
	v_mov_b32_e32 v132, v2
	v_mov_b32_e32 v133, v3
	v_mov_b32_e32 v134, v4
	v_mov_b32_e32 v135, v5
	v_mov_b32_e32 v136, v6
	v_mov_b32_e32 v137, v7
	v_mov_b32_e32 v138, v8
	v_mov_b32_e32 v139, v9
	v_mov_b32_e32 v140, v10
	v_mov_b32_e32 v141, v11
	v_mov_b32_e32 v142, v12
	v_mov_b32_e32 v143, v13
	v_mov_b32_e32 v150, v14
	v_mov_b32_e32 v151, v15
	s_mov_b32 s32, 0
	s_mov_b32 s16, s30
	s_mov_b32 s17, s31
	s_waitcnt lgkmcnt(0)
	s_barrier
	s_branch .Lg4b_epi
